# SP1 load segments: all four DMAs issued after the first 8 ds_reads (before the A-fragment reads)
# baseline (speedup 1.0000x reference)
; #define PG8_STAGE(bufoff, gbase, voff) do { _Pragma("unroll") for (int _i = 0; _i < 2; ++_i) \
;         __builtin_amdgcn_global_load_lds((const unsigned*)((const char*)(gbase) + (voff)[_i]), (PG8_LAS unsigned*)(lds + (bufoff) + ldsw + _i * 8192), 16, 0, 0); } while (0)
; #define PG8_LDA(dst, b, h) do { _Pragma("unroll") for (int m = 0; m < 4; ++m) _Pragma("unroll") for (int k = 0; k < 2; ++k) dst[m][k] = *(const PG8_LAS bf16x8*)(lds + PG8_SA(b, h) + aoff + m * 2048 + k * 1024); } while (0)
; #define PG8_LDB(dst, b, h) do { _Pragma("unroll") for (int n = 0; n < 2; ++n) _Pragma("unroll") for (int k = 0; k < 2; ++k) dst[n][k] = *(const PG8_LAS bf16x8*)(lds + PG8_SB(b, h) + boff + n * 2048 + k * 1024); } while (0)
; #define PG8_MMA(ai, bj, At, Bt) do { __builtin_amdgcn_s_setprio(1); _Pragma("unroll") for (int m = 0; m < 4; ++m) _Pragma("unroll") for (int n = 0; n < 2; ++n) _Pragma("unroll") for (int k = 0; k < 2; ++k) \
;         acc[ai][bj][m][n] = __builtin_amdgcn_mfma_f32_16x16x32_bf16(Bt[n][k], At[m][k], acc[ai][bj][m][n], 0, 0, 0); __builtin_amdgcn_s_setprio(0); } while (0)
; #define PG8_WAIT_V(n) asm volatile("s_waitcnt vmcnt(" #n ")" ::: "memory")
; #define PG8_WAIT_L(n) asm volatile("s_waitcnt lgkmcnt(" #n ")" ::: "memory")
; #define PG8_BAR __builtin_amdgcn_s_barrier()
; #define PG8_SCHED __builtin_amdgcn_sched_barrier(0)
; template <class Epi, class Sched, bool ALIGN_EPI = false, bool SP2 = false>
; __device__ __forceinline__ void gemm_phase(PG8_LAS unsigned char* lds, const Gemm g, const Sched& S, const Epi& E) {
;     ...
;             PG8_LDB(B0, 0, 0); PG8_LDB(B1, 0, 1); PG8_SCHED; PG8_LDA(At, 0, 0); PG8_STAGE(PG8_SA(1, 1), a1 + hstep, voffA);
;             PG8_WAIT_V(8); PG8_WAIT_L(0); PG8_BAR; PG8_MMA(0, 0, At, B0); PG8_MMA(0, 1, At, B1); PG8_BAR; PG8_SCHED;
;             PG8_LDA(At, 0, 1); PG8_STAGE(PG8_SB(0, 0), b2, voffB); PG8_STAGE(PG8_SB(0, 1), b2 + hstep, voffB); PG8_STAGE(PG8_SA(0, 0), a2, voffA);
;             PG8_WAIT_V(8); PG8_WAIT_L(0); PG8_BAR; PG8_MMA(1, 0, At, B0); PG8_MMA(1, 1, At, B1); PG8_BAR; PG8_SCHED;
.LBB0_150:
	ds_read_b128 v[144:147], v155
	ds_read_b128 v[148:151], v155 offset:1024
	ds_read_b128 v[160:163], v155 offset:2048
	ds_read_b128 v[164:167], v155 offset:3072
	ds_read_b128 v[168:171], v156
	ds_read_b128 v[172:175], v156 offset:1024
	ds_read_b128 v[176:179], v156 offset:2048
	ds_read_b128 v[180:183], v156 offset:3072
	s_mov_b32 m0, s48
	s_nop 0
	global_load_lds_dwordx4 v[250:251], off
	s_mov_b32 m0, s49
	s_nop 0
	global_load_lds_dwordx4 v[252:253], off
	s_add_u32 s30, s28, 0xfff80080
	s_addc_u32 s31, s29, -1
	s_cmp_eq_u32 s60, 28
	s_cselect_b32 s35, s15, s31
	s_cselect_b32 s34, s56, s30
	s_cselect_b32 s31, s13, s59
	s_cselect_b32 s30, s57, s58
	v_lshl_add_u64 v[216:217], s[28:29], 0, v[136:137]
	s_add_i32 m0, s25, 0xc000
	s_nop 0
	global_load_lds_dwordx4 v[216:217], off
	v_lshl_add_u64 v[216:217], s[28:29], 0, v[138:139]
	s_add_i32 m0, s25, 0xe000
	s_nop 0
	global_load_lds_dwordx4 v[216:217], off
	ds_read_b128 v[184:187], v157
	ds_read_b128 v[188:191], v157 offset:1024
	ds_read_b128 v[192:195], v157 offset:2048
	ds_read_b128 v[196:199], v157 offset:3072
	ds_read_b128 v[200:203], v157 offset:4096
	ds_read_b128 v[204:207], v157 offset:5120
	ds_read_b128 v[208:211], v157 offset:6144
	ds_read_b128 v[212:215], v157 offset:7168
	s_waitcnt vmcnt(8)
	s_waitcnt lgkmcnt(0)
	s_barrier
	s_waitcnt lgkmcnt(0)
	v_mfma_f32_16x16x32_bf16 v[124:127], v[144:147], v[184:187], v[124:127]
	v_mfma_f32_16x16x32_bf16 v[120:123], v[160:163], v[184:187], v[120:123]
	s_add_u32 s62, s30, 0x80000
	v_mfma_f32_16x16x32_bf16 v[108:111], v[144:147], v[192:195], v[108:111]
	v_mfma_f32_16x16x32_bf16 v[104:107], v[160:163], v[192:195], v[104:107]
	s_addc_u32 s63, s31, 0
	v_mfma_f32_16x16x32_bf16 v[92:95], v[144:147], v[200:203], v[92:95]
	v_mfma_f32_16x16x32_bf16 v[88:91], v[160:163], v[200:203], v[88:91]
	v_lshl_add_u64 v[216:217], s[30:31], 0, v[132:133]
	v_mfma_f32_16x16x32_bf16 v[76:79], v[144:147], v[208:211], v[76:79]
	v_mfma_f32_16x16x32_bf16 v[72:75], v[160:163], v[208:211], v[72:75]
	v_lshl_add_u64 v[218:219], s[30:31], 0, v[128:129]
	v_mfma_f32_16x16x32_bf16 v[124:127], v[148:151], v[188:191], v[124:127]
	v_mfma_f32_16x16x32_bf16 v[120:123], v[164:167], v[188:191], v[120:123]
	v_lshl_add_u64 v[246:247], s[62:63], 0, v[132:133]
	v_mfma_f32_16x16x32_bf16 v[108:111], v[148:151], v[196:199], v[108:111]
	v_mfma_f32_16x16x32_bf16 v[104:107], v[164:167], v[196:199], v[104:107]
	v_lshl_add_u64 v[222:223], s[34:35], 0, v[130:131]
	v_mfma_f32_16x16x32_bf16 v[92:95], v[148:151], v[204:207], v[92:95]
	v_mfma_f32_16x16x32_bf16 v[88:91], v[164:167], v[204:207], v[88:91]
	v_lshl_add_u64 v[248:249], s[62:63], 0, v[128:129]
	v_mfma_f32_16x16x32_bf16 v[76:79], v[148:151], v[212:215], v[76:79]
	v_mfma_f32_16x16x32_bf16 v[72:75], v[164:167], v[212:215], v[72:75]
	v_lshl_add_u64 v[220:221], s[34:35], 0, v[134:135]
	v_mfma_f32_16x16x32_bf16 v[116:119], v[168:171], v[184:187], v[116:119]
	v_mfma_f32_16x16x32_bf16 v[112:115], v[176:179], v[184:187], v[112:115]
	v_mfma_f32_16x16x32_bf16 v[100:103], v[168:171], v[192:195], v[100:103]
	v_mfma_f32_16x16x32_bf16 v[96:99], v[176:179], v[192:195], v[96:99]
	v_mfma_f32_16x16x32_bf16 v[84:87], v[168:171], v[200:203], v[84:87]
	v_mfma_f32_16x16x32_bf16 v[80:83], v[176:179], v[200:203], v[80:83]
	v_mfma_f32_16x16x32_bf16 v[68:71], v[168:171], v[208:211], v[68:71]
	v_mfma_f32_16x16x32_bf16 v[64:67], v[176:179], v[208:211], v[64:67]
	v_mfma_f32_16x16x32_bf16 v[116:119], v[172:175], v[188:191], v[116:119]
	v_mfma_f32_16x16x32_bf16 v[112:115], v[180:183], v[188:191], v[112:115]
	v_mfma_f32_16x16x32_bf16 v[100:103], v[172:175], v[196:199], v[100:103]
	v_mfma_f32_16x16x32_bf16 v[96:99], v[180:183], v[196:199], v[96:99]
	v_mfma_f32_16x16x32_bf16 v[84:87], v[172:175], v[204:207], v[84:87]
	v_mfma_f32_16x16x32_bf16 v[80:83], v[180:183], v[204:207], v[80:83]
	v_mfma_f32_16x16x32_bf16 v[68:71], v[172:175], v[212:215], v[68:71]
	v_mfma_f32_16x16x32_bf16 v[64:67], v[180:183], v[212:215], v[64:67]
	s_add_i32 s61, s52, s42
	s_mov_b32 m0, s61
	s_barrier
	global_load_lds_dwordx4 v[216:217], off
	s_add_i32 m0, s61, 0x2000
	s_add_i32 s61, s53, s42
	global_load_lds_dwordx4 v[218:219], off
	s_mov_b32 m0, s61
	s_nop 0
	global_load_lds_dwordx4 v[246:247], off
	s_add_i32 m0, s61, 0x2000
	s_nop 0
	global_load_lds_dwordx4 v[248:249], off
	ds_read_b128 v[184:187], v157 offset:16384
	ds_read_b128 v[188:191], v157 offset:17408
	ds_read_b128 v[192:195], v157 offset:18432
	ds_read_b128 v[196:199], v157 offset:19456
	ds_read_b128 v[200:203], v157 offset:20480
	ds_read_b128 v[204:207], v157 offset:21504
	ds_read_b128 v[208:211], v157 offset:22528
	ds_read_b128 v[212:215], v157 offset:23552
	s_waitcnt vmcnt(6)
	s_waitcnt lgkmcnt(0)
	s_barrier
; #define PG8_STAGE(bufoff, gbase, voff) do { _Pragma("unroll") for (int _i = 0; _i < 2; ++_i) \
;         __builtin_amdgcn_global_load_lds((const unsigned*)((const char*)(gbase) + (voff)[_i]), (PG8_LAS unsigned*)(lds + (bufoff) + ldsw + _i * 8192), 16, 0, 0); } while (0)
; #define PG8_LDA(dst, b, h) do { _Pragma("unroll") for (int m = 0; m < 4; ++m) _Pragma("unroll") for (int k = 0; k < 2; ++k) dst[m][k] = *(const PG8_LAS bf16x8*)(lds + PG8_SA(b, h) + aoff + m * 2048 + k * 1024); } while (0)
; #define PG8_LDB(dst, b, h) do { _Pragma("unroll") for (int n = 0; n < 2; ++n) _Pragma("unroll") for (int k = 0; k < 2; ++k) dst[n][k] = *(const PG8_LAS bf16x8*)(lds + PG8_SB(b, h) + boff + n * 2048 + k * 1024); } while (0)
; #define PG8_MMA(ai, bj, At, Bt) do { __builtin_amdgcn_s_setprio(1); _Pragma("unroll") for (int m = 0; m < 4; ++m) _Pragma("unroll") for (int n = 0; n < 2; ++n) _Pragma("unroll") for (int k = 0; k < 2; ++k) \
;         acc[ai][bj][m][n] = __builtin_amdgcn_mfma_f32_16x16x32_bf16(Bt[n][k], At[m][k], acc[ai][bj][m][n], 0, 0, 0); __builtin_amdgcn_s_setprio(0); } while (0)
; #define PG8_WAIT_V(n) asm volatile("s_waitcnt vmcnt(" #n ")" ::: "memory")
; #define PG8_WAIT_L(n) asm volatile("s_waitcnt lgkmcnt(" #n ")" ::: "memory")
; #define PG8_BAR __builtin_amdgcn_s_barrier()
; #define PG8_SCHED __builtin_amdgcn_sched_barrier(0)
; template <class Epi, class Sched, bool ALIGN_EPI = false, bool SP2 = false>
; __device__ __forceinline__ void gemm_phase(PG8_LAS unsigned char* lds, const Gemm g, const Sched& S, const Epi& E) {
;     ...
;             PG8_WAIT_V(8); PG8_WAIT_L(0); PG8_BAR; PG8_MMA(1, 0, At, B0); PG8_MMA(1, 1, At, B1); PG8_BAR; PG8_SCHED;
;             PG8_LDB(B0, 1, 0); PG8_LDB(B1, 1, 1); PG8_SCHED; PG8_LDA(At, 1, 0); PG8_STAGE(PG8_SA(0, 1), a2 + hstep, voffA);
;             PG8_WAIT_V(8); PG8_WAIT_L(0); PG8_BAR; PG8_MMA(0, 0, At, B0); PG8_MMA(0, 1, At, B1); PG8_BAR; PG8_SCHED;
	s_waitcnt lgkmcnt(0)
	v_mfma_f32_16x16x32_bf16 v[60:63], v[144:147], v[184:187], v[60:63]
	v_mfma_f32_16x16x32_bf16 v[56:59], v[160:163], v[184:187], v[56:59]
	v_mfma_f32_16x16x32_bf16 v[44:47], v[144:147], v[192:195], v[44:47]
	v_mfma_f32_16x16x32_bf16 v[40:43], v[160:163], v[192:195], v[40:43]
	v_mfma_f32_16x16x32_bf16 v[28:31], v[144:147], v[200:203], v[28:31]
	v_mfma_f32_16x16x32_bf16 v[24:27], v[160:163], v[200:203], v[24:27]
	v_mfma_f32_16x16x32_bf16 v[12:15], v[144:147], v[208:211], v[12:15]
	v_mfma_f32_16x16x32_bf16 v[8:11], v[160:163], v[208:211], v[8:11]
	v_mfma_f32_16x16x32_bf16 v[60:63], v[148:151], v[188:191], v[60:63]
	v_mfma_f32_16x16x32_bf16 v[56:59], v[164:167], v[188:191], v[56:59]
	v_mfma_f32_16x16x32_bf16 v[44:47], v[148:151], v[196:199], v[44:47]
	v_mfma_f32_16x16x32_bf16 v[40:43], v[164:167], v[196:199], v[40:43]
	v_mfma_f32_16x16x32_bf16 v[28:31], v[148:151], v[204:207], v[28:31]
	v_mfma_f32_16x16x32_bf16 v[24:27], v[164:167], v[204:207], v[24:27]
	v_mfma_f32_16x16x32_bf16 v[12:15], v[148:151], v[212:215], v[12:15]
	v_mfma_f32_16x16x32_bf16 v[8:11], v[164:167], v[212:215], v[8:11]
	v_mfma_f32_16x16x32_bf16 v[52:55], v[168:171], v[184:187], v[52:55]
	v_mfma_f32_16x16x32_bf16 v[48:51], v[176:179], v[184:187], v[48:51]
	v_mfma_f32_16x16x32_bf16 v[36:39], v[168:171], v[192:195], v[36:39]
	v_mfma_f32_16x16x32_bf16 v[32:35], v[176:179], v[192:195], v[32:35]
	v_mfma_f32_16x16x32_bf16 v[20:23], v[168:171], v[200:203], v[20:23]
	v_mfma_f32_16x16x32_bf16 v[16:19], v[176:179], v[200:203], v[16:19]
	v_mfma_f32_16x16x32_bf16 v[4:7], v[168:171], v[208:211], v[4:7]
	v_mfma_f32_16x16x32_bf16 v[0:3], v[176:179], v[208:211], v[0:3]
	v_mfma_f32_16x16x32_bf16 v[52:55], v[172:175], v[188:191], v[52:55]
	v_mfma_f32_16x16x32_bf16 v[48:51], v[180:183], v[188:191], v[48:51]
	v_mfma_f32_16x16x32_bf16 v[36:39], v[172:175], v[196:199], v[36:39]
	v_mfma_f32_16x16x32_bf16 v[32:35], v[180:183], v[196:199], v[32:35]
	v_mfma_f32_16x16x32_bf16 v[20:23], v[172:175], v[204:207], v[20:23]
	v_mfma_f32_16x16x32_bf16 v[16:19], v[180:183], v[204:207], v[16:19]
	v_mfma_f32_16x16x32_bf16 v[4:7], v[172:175], v[212:215], v[4:7]
	v_mfma_f32_16x16x32_bf16 v[0:3], v[180:183], v[212:215], v[0:3]
	s_barrier
	s_add_i32 s61, 0, 0x18000
	s_add_i32 s62, 0, 0x1c000
	v_add_u32_e32 v164, s61, v153
	v_add_u32_e32 v180, s62, v153
	ds_read_b128 v[144:147], v164
	ds_read_b128 v[148:151], v164 offset:1024
	ds_read_b128 v[160:163], v164 offset:2048
	ds_read_b128 v[164:167], v164 offset:3072
	ds_read_b128 v[168:171], v180
	ds_read_b128 v[172:175], v180 offset:1024
	ds_read_b128 v[176:179], v180 offset:2048
	ds_read_b128 v[180:183], v180 offset:3072
	s_mov_b32 m0, s25
	s_nop 0
	global_load_lds_dwordx4 v[220:221], off
	s_mov_b32 m0, s45
	s_nop 0
	global_load_lds_dwordx4 v[222:223], off
	s_add_u32 s34, s34, 0x80000
	s_addc_u32 s35, s35, 0
	s_mov_b32 m0, s46
	v_lshl_add_u64 v[224:225], s[34:35], 0, v[134:135]
	global_load_lds_dwordx4 v[224:225], off
	v_lshl_add_u64 v[224:225], s[34:35], 0, v[130:131]
	s_mov_b32 m0, s47
	s_nop 0
	global_load_lds_dwordx4 v[224:225], off
	ds_read_b128 v[184:187], v157 offset:32768
	ds_read_b128 v[188:191], v157 offset:33792
	ds_read_b128 v[192:195], v157 offset:34816
	ds_read_b128 v[196:199], v157 offset:35840
	ds_read_b128 v[200:203], v157 offset:36864
	ds_read_b128 v[204:207], v157 offset:37888
	ds_read_b128 v[208:211], v157 offset:38912
	ds_read_b128 v[212:215], v157 offset:39936
	s_waitcnt vmcnt(8)
	s_waitcnt lgkmcnt(0)
	s_barrier
; #define PG8_STAGE(bufoff, gbase, voff) do { _Pragma("unroll") for (int _i = 0; _i < 2; ++_i) \
;         __builtin_amdgcn_global_load_lds((const unsigned*)((const char*)(gbase) + (voff)[_i]), (PG8_LAS unsigned*)(lds + (bufoff) + ldsw + _i * 8192), 16, 0, 0); } while (0)
; #define PG8_LDA(dst, b, h) do { _Pragma("unroll") for (int m = 0; m < 4; ++m) _Pragma("unroll") for (int k = 0; k < 2; ++k) dst[m][k] = *(const PG8_LAS bf16x8*)(lds + PG8_SA(b, h) + aoff + m * 2048 + k * 1024); } while (0)
; #define PG8_MMA(ai, bj, At, Bt) do { __builtin_amdgcn_s_setprio(1); _Pragma("unroll") for (int m = 0; m < 4; ++m) _Pragma("unroll") for (int n = 0; n < 2; ++n) _Pragma("unroll") for (int k = 0; k < 2; ++k) \
;         acc[ai][bj][m][n] = __builtin_amdgcn_mfma_f32_16x16x32_bf16(Bt[n][k], At[m][k], acc[ai][bj][m][n], 0, 0, 0); __builtin_amdgcn_s_setprio(0); } while (0)
; #define PG8_WAIT_V(n) asm volatile("s_waitcnt vmcnt(" #n ")" ::: "memory")
; #define PG8_WAIT_L(n) asm volatile("s_waitcnt lgkmcnt(" #n ")" ::: "memory")
; #define PG8_BAR __builtin_amdgcn_s_barrier()
; #define PG8_SCHED __builtin_amdgcn_sched_barrier(0)
; template <class Epi, class Sched, bool ALIGN_EPI = false, bool SP2 = false>
; __device__ __forceinline__ void gemm_phase(PG8_LAS unsigned char* lds, const Gemm g, const Sched& S, const Epi& E) {
;     ...
;         for (int t = 0; t < nt; t += 2) {
;     ...
;             PG8_WAIT_V(8); PG8_WAIT_L(0); PG8_BAR; PG8_MMA(0, 0, At, B0); PG8_MMA(0, 1, At, B1); PG8_BAR; PG8_SCHED;
;             PG8_LDA(At, 1, 1); PG8_STAGE(PG8_SB(1, 0), b3, voffB); PG8_STAGE(PG8_SB(1, 1), b3 + hstep, voffB); PG8_STAGE(PG8_SA(1, 0), a3, voffA);
;             PG8_WAIT_V(8); PG8_WAIT_L(0); PG8_BAR; PG8_MMA(1, 0, At, B0); PG8_MMA(1, 1, At, B1); PG8_BAR; PG8_SCHED;
	s_waitcnt lgkmcnt(0)
	v_mfma_f32_16x16x32_bf16 v[124:127], v[144:147], v[184:187], v[124:127]
	v_mfma_f32_16x16x32_bf16 v[120:123], v[160:163], v[184:187], v[120:123]
	s_add_u32 s30, s30, 0x80080
	v_mfma_f32_16x16x32_bf16 v[108:111], v[144:147], v[192:195], v[108:111]
	v_mfma_f32_16x16x32_bf16 v[104:107], v[160:163], v[192:195], v[104:107]
	s_addc_u32 s31, s31, 0
	v_mfma_f32_16x16x32_bf16 v[92:95], v[144:147], v[200:203], v[92:95]
	v_mfma_f32_16x16x32_bf16 v[88:91], v[160:163], v[200:203], v[88:91]
	v_lshl_add_u64 v[216:217], v[216:217], 0, s[8:9]
	v_mfma_f32_16x16x32_bf16 v[76:79], v[144:147], v[208:211], v[76:79]
	v_mfma_f32_16x16x32_bf16 v[72:75], v[160:163], v[208:211], v[72:75]
	v_lshl_add_u64 v[218:219], v[218:219], 0, s[8:9]
	v_mfma_f32_16x16x32_bf16 v[124:127], v[148:151], v[188:191], v[124:127]
	v_mfma_f32_16x16x32_bf16 v[120:123], v[164:167], v[188:191], v[120:123]
	v_lshl_add_u64 v[246:247], s[30:31], 0, v[132:133]
	v_mfma_f32_16x16x32_bf16 v[108:111], v[148:151], v[196:199], v[108:111]
	v_mfma_f32_16x16x32_bf16 v[104:107], v[164:167], v[196:199], v[104:107]
	v_lshl_add_u64 v[248:249], s[30:31], 0, v[128:129]
	v_mfma_f32_16x16x32_bf16 v[92:95], v[148:151], v[204:207], v[92:95]
	v_mfma_f32_16x16x32_bf16 v[88:91], v[164:167], v[204:207], v[88:91]
	v_lshl_add_u64 v[250:251], v[220:221], 0, s[8:9]
	v_mfma_f32_16x16x32_bf16 v[76:79], v[148:151], v[212:215], v[76:79]
	v_mfma_f32_16x16x32_bf16 v[72:75], v[164:167], v[212:215], v[72:75]
	v_lshl_add_u64 v[252:253], v[222:223], 0, s[8:9]
	v_mfma_f32_16x16x32_bf16 v[116:119], v[168:171], v[184:187], v[116:119]
	v_mfma_f32_16x16x32_bf16 v[112:115], v[176:179], v[184:187], v[112:115]
	v_mfma_f32_16x16x32_bf16 v[100:103], v[168:171], v[192:195], v[100:103]
	v_mfma_f32_16x16x32_bf16 v[96:99], v[176:179], v[192:195], v[96:99]
	v_mfma_f32_16x16x32_bf16 v[84:87], v[168:171], v[200:203], v[84:87]
	v_mfma_f32_16x16x32_bf16 v[80:83], v[176:179], v[200:203], v[80:83]
	v_mfma_f32_16x16x32_bf16 v[68:71], v[168:171], v[208:211], v[68:71]
	v_mfma_f32_16x16x32_bf16 v[64:67], v[176:179], v[208:211], v[64:67]
	v_mfma_f32_16x16x32_bf16 v[116:119], v[172:175], v[188:191], v[116:119]
	v_mfma_f32_16x16x32_bf16 v[112:115], v[180:183], v[188:191], v[112:115]
	v_mfma_f32_16x16x32_bf16 v[100:103], v[172:175], v[196:199], v[100:103]
	v_mfma_f32_16x16x32_bf16 v[96:99], v[180:183], v[196:199], v[96:99]
	v_mfma_f32_16x16x32_bf16 v[84:87], v[172:175], v[204:207], v[84:87]
	v_mfma_f32_16x16x32_bf16 v[80:83], v[180:183], v[204:207], v[80:83]
	v_mfma_f32_16x16x32_bf16 v[68:71], v[172:175], v[212:215], v[68:71]
	v_mfma_f32_16x16x32_bf16 v[64:67], v[180:183], v[212:215], v[64:67]
	s_add_i32 s34, s61, s42
	s_mov_b32 m0, s34
	s_barrier
	global_load_lds_dwordx4 v[216:217], off
	s_add_i32 m0, s34, 0x2000
	s_add_i32 s34, s62, s42
	global_load_lds_dwordx4 v[218:219], off
	s_mov_b32 m0, s34
	s_nop 0
	global_load_lds_dwordx4 v[246:247], off
	s_add_i32 m0, s34, 0x2000
	s_nop 0
	global_load_lds_dwordx4 v[248:249], off
	ds_read_b128 v[184:187], v157 offset:49152
	ds_read_b128 v[188:191], v157 offset:50176
	ds_read_b128 v[192:195], v157 offset:51200
	ds_read_b128 v[196:199], v157 offset:52224
	ds_read_b128 v[200:203], v157 offset:53248
	ds_read_b128 v[204:207], v157 offset:54272
	ds_read_b128 v[208:211], v157 offset:55296
	ds_read_b128 v[212:215], v157 offset:56320
	s_waitcnt vmcnt(6)
	s_waitcnt lgkmcnt(0)
	s_barrier
	s_waitcnt lgkmcnt(0)
	v_mfma_f32_16x16x32_bf16 v[60:63], v[144:147], v[184:187], v[60:63]
	v_mfma_f32_16x16x32_bf16 v[56:59], v[160:163], v[184:187], v[56:59]
	v_mfma_f32_16x16x32_bf16 v[44:47], v[144:147], v[192:195], v[44:47]
	v_mfma_f32_16x16x32_bf16 v[40:43], v[160:163], v[192:195], v[40:43]
	v_mfma_f32_16x16x32_bf16 v[28:31], v[144:147], v[200:203], v[28:31]
	v_mfma_f32_16x16x32_bf16 v[24:27], v[160:163], v[200:203], v[24:27]
	v_mfma_f32_16x16x32_bf16 v[12:15], v[144:147], v[208:211], v[12:15]
	v_mfma_f32_16x16x32_bf16 v[8:11], v[160:163], v[208:211], v[8:11]
	v_mfma_f32_16x16x32_bf16 v[60:63], v[148:151], v[188:191], v[60:63]
	v_mfma_f32_16x16x32_bf16 v[56:59], v[164:167], v[188:191], v[56:59]
	v_mfma_f32_16x16x32_bf16 v[44:47], v[148:151], v[196:199], v[44:47]
	v_mfma_f32_16x16x32_bf16 v[40:43], v[164:167], v[196:199], v[40:43]
	v_mfma_f32_16x16x32_bf16 v[28:31], v[148:151], v[204:207], v[28:31]
	v_mfma_f32_16x16x32_bf16 v[24:27], v[164:167], v[204:207], v[24:27]
	v_mfma_f32_16x16x32_bf16 v[12:15], v[148:151], v[212:215], v[12:15]
	v_mfma_f32_16x16x32_bf16 v[8:11], v[164:167], v[212:215], v[8:11]
	v_mfma_f32_16x16x32_bf16 v[52:55], v[168:171], v[184:187], v[52:55]
	v_mfma_f32_16x16x32_bf16 v[48:51], v[176:179], v[184:187], v[48:51]
	v_mfma_f32_16x16x32_bf16 v[36:39], v[168:171], v[192:195], v[36:39]
	v_mfma_f32_16x16x32_bf16 v[32:35], v[176:179], v[192:195], v[32:35]
	s_add_i32 s60, s60, 2
	v_mfma_f32_16x16x32_bf16 v[20:23], v[168:171], v[200:203], v[20:23]
	v_mfma_f32_16x16x32_bf16 v[16:19], v[176:179], v[200:203], v[16:19]
	s_add_u32 s28, s28, 0x100
	v_mfma_f32_16x16x32_bf16 v[4:7], v[168:171], v[208:211], v[4:7]
	v_mfma_f32_16x16x32_bf16 v[0:3], v[176:179], v[208:211], v[0:3]
	s_addc_u32 s29, s29, 0
	v_mfma_f32_16x16x32_bf16 v[52:55], v[172:175], v[188:191], v[52:55]
	v_mfma_f32_16x16x32_bf16 v[48:51], v[180:183], v[188:191], v[48:51]
	s_add_u32 s58, s58, 0x100
	v_mfma_f32_16x16x32_bf16 v[36:39], v[172:175], v[196:199], v[36:39]
	v_mfma_f32_16x16x32_bf16 v[32:35], v[180:183], v[196:199], v[32:35]
	s_addc_u32 s59, s59, 0
	v_mfma_f32_16x16x32_bf16 v[20:23], v[172:175], v[204:207], v[20:23]
	v_mfma_f32_16x16x32_bf16 v[16:19], v[180:183], v[204:207], v[16:19]
	v_mfma_f32_16x16x32_bf16 v[4:7], v[172:175], v[212:215], v[4:7]
	v_mfma_f32_16x16x32_bf16 v[0:3], v[180:183], v[212:215], v[0:3]
	s_barrier
	s_cmp_gt_u32 s60, 29
	s_cbranch_scc0 .LBB0_150
	s_and_b64 vcc, exec, s[10:11]
	s_cbranch_vccz .LBB0_153
	s_barrier

; #define PG8_STAGE(bufoff, gbase, voff) do { _Pragma("unroll") for (int _i = 0; _i < 2; ++_i) \
;         __builtin_amdgcn_global_load_lds((const unsigned*)((const char*)(gbase) + (voff)[_i]), (PG8_LAS unsigned*)(lds + (bufoff) + ldsw + _i * 8192), 16, 0, 0); } while (0)
; #define PG8_LDA(dst, b, h) do { _Pragma("unroll") for (int m = 0; m < 4; ++m) _Pragma("unroll") for (int k = 0; k < 2; ++k) dst[m][k] = *(const PG8_LAS bf16x8*)(lds + PG8_SA(b, h) + aoff + m * 2048 + k * 1024); } while (0)
; #define PG8_LDB(dst, b, h) do { _Pragma("unroll") for (int n = 0; n < 2; ++n) _Pragma("unroll") for (int k = 0; k < 2; ++k) dst[n][k] = *(const PG8_LAS bf16x8*)(lds + PG8_SB(b, h) + boff + n * 2048 + k * 1024); } while (0)
; #define PG8_MMA(ai, bj, At, Bt) do { __builtin_amdgcn_s_setprio(1); _Pragma("unroll") for (int m = 0; m < 4; ++m) _Pragma("unroll") for (int n = 0; n < 2; ++n) _Pragma("unroll") for (int k = 0; k < 2; ++k) \
;         acc[ai][bj][m][n] = __builtin_amdgcn_mfma_f32_16x16x32_bf16(Bt[n][k], At[m][k], acc[ai][bj][m][n], 0, 0, 0); __builtin_amdgcn_s_setprio(0); } while (0)
; #define PG8_WAIT_V(n) asm volatile("s_waitcnt vmcnt(" #n ")" ::: "memory")
; #define PG8_WAIT_L(n) asm volatile("s_waitcnt lgkmcnt(" #n ")" ::: "memory")
; #define PG8_BAR __builtin_amdgcn_s_barrier()
; #define PG8_SCHED __builtin_amdgcn_sched_barrier(0)
; template <class Epi, class Sched, bool ALIGN_EPI = false, bool SP2 = false>
; __device__ __forceinline__ void gemm_phase(PG8_LAS unsigned char* lds, const Gemm g, const Sched& S, const Epi& E) {
;     ...
;             PG8_LDB(B0, 0, 0); PG8_LDB(B1, 0, 1); PG8_SCHED; PG8_LDA(At, 0, 0); PG8_STAGE(PG8_SA(1, 1), a1 + hstep, voffA);
;             PG8_WAIT_V(8); PG8_WAIT_L(0); PG8_BAR; PG8_MMA(0, 0, At, B0); PG8_MMA(0, 1, At, B1); PG8_BAR; PG8_SCHED;
;             PG8_LDA(At, 0, 1); PG8_STAGE(PG8_SB(0, 0), b2, voffB); PG8_STAGE(PG8_SB(0, 1), b2 + hstep, voffB); PG8_STAGE(PG8_SA(0, 0), a2, voffA);
;             PG8_WAIT_V(8); PG8_WAIT_L(0); PG8_BAR; PG8_MMA(1, 0, At, B0); PG8_MMA(1, 1, At, B1); PG8_BAR; PG8_SCHED;
.LBB0_621:
	ds_read_b128 v[128:131], v189
	ds_read_b128 v[132:135], v189 offset:1024
	ds_read_b128 v[136:139], v189 offset:2048
	ds_read_b128 v[140:143], v189 offset:3072
	ds_read_b128 v[144:147], v190
	ds_read_b128 v[148:151], v190 offset:1024
	ds_read_b128 v[168:171], v190 offset:2048
	ds_read_b128 v[172:175], v190 offset:3072
	s_mov_b32 m0, s50
	s_nop 0
	global_load_lds_dwordx4 v[250:251], off
	s_mov_b32 m0, s51
	s_nop 0
	global_load_lds_dwordx4 v[252:253], off
	s_add_u32 s36, s34, 0xfff80080
	s_addc_u32 s37, s35, -1
	s_cmp_eq_u32 s60, 28
	s_cselect_b32 s39, s17, s37
	s_cselect_b32 s38, s29, s36
	s_cselect_b32 s37, s15, s59
	s_cselect_b32 s36, s57, s58
	v_lshl_add_u64 v[184:185], s[34:35], 0, v[160:161]
	s_add_i32 m0, s31, 0xc000
	s_nop 0
	global_load_lds_dwordx4 v[184:185], off
	v_lshl_add_u64 v[184:185], s[34:35], 0, v[162:163]
	s_add_i32 m0, s31, 0xe000
	s_nop 0
	global_load_lds_dwordx4 v[184:185], off
	ds_read_b128 v[176:179], v191
	ds_read_b128 v[180:183], v191 offset:1024
	ds_read_b128 v[192:195], v191 offset:2048
	ds_read_b128 v[196:199], v191 offset:3072
	ds_read_b128 v[200:203], v191 offset:4096
	ds_read_b128 v[204:207], v191 offset:5120
	ds_read_b128 v[208:211], v191 offset:6144
	ds_read_b128 v[212:215], v191 offset:7168
	s_waitcnt vmcnt(8)
	s_waitcnt lgkmcnt(0)
	s_barrier
	s_waitcnt lgkmcnt(0)
	v_mfma_f32_16x16x32_bf16 v[124:127], v[128:131], v[176:179], v[124:127]
	v_mfma_f32_16x16x32_bf16 v[120:123], v[136:139], v[176:179], v[120:123]
	s_add_u32 s62, s36, 0x80000
	v_mfma_f32_16x16x32_bf16 v[108:111], v[128:131], v[192:195], v[108:111]
	v_mfma_f32_16x16x32_bf16 v[104:107], v[136:139], v[192:195], v[104:107]
	s_addc_u32 s63, s37, 0
	v_mfma_f32_16x16x32_bf16 v[92:95], v[128:131], v[200:203], v[92:95]
	v_mfma_f32_16x16x32_bf16 v[88:91], v[136:139], v[200:203], v[88:91]
	v_lshl_add_u64 v[184:185], s[36:37], 0, v[154:155]
	v_mfma_f32_16x16x32_bf16 v[76:79], v[128:131], v[208:211], v[76:79]
	v_mfma_f32_16x16x32_bf16 v[72:75], v[136:139], v[208:211], v[72:75]
	v_lshl_add_u64 v[216:217], s[36:37], 0, v[158:159]
	v_mfma_f32_16x16x32_bf16 v[124:127], v[132:135], v[180:183], v[124:127]
	v_mfma_f32_16x16x32_bf16 v[120:123], v[140:143], v[180:183], v[120:123]
	v_lshl_add_u64 v[246:247], s[62:63], 0, v[154:155]
	v_mfma_f32_16x16x32_bf16 v[108:111], v[132:135], v[196:199], v[108:111]
	v_mfma_f32_16x16x32_bf16 v[104:107], v[140:143], v[196:199], v[104:107]
	v_lshl_add_u64 v[220:221], s[38:39], 0, v[156:157]
	v_mfma_f32_16x16x32_bf16 v[92:95], v[132:135], v[204:207], v[92:95]
	v_mfma_f32_16x16x32_bf16 v[88:91], v[140:143], v[204:207], v[88:91]
	v_lshl_add_u64 v[248:249], s[62:63], 0, v[158:159]
	v_mfma_f32_16x16x32_bf16 v[76:79], v[132:135], v[212:215], v[76:79]
	v_mfma_f32_16x16x32_bf16 v[72:75], v[140:143], v[212:215], v[72:75]
	v_lshl_add_u64 v[218:219], s[38:39], 0, v[152:153]
	v_mfma_f32_16x16x32_bf16 v[116:119], v[144:147], v[176:179], v[116:119]
	v_mfma_f32_16x16x32_bf16 v[112:115], v[168:171], v[176:179], v[112:115]
	v_mfma_f32_16x16x32_bf16 v[100:103], v[144:147], v[192:195], v[100:103]
	v_mfma_f32_16x16x32_bf16 v[96:99], v[168:171], v[192:195], v[96:99]
	v_mfma_f32_16x16x32_bf16 v[84:87], v[144:147], v[200:203], v[84:87]
	v_mfma_f32_16x16x32_bf16 v[80:83], v[168:171], v[200:203], v[80:83]
	v_mfma_f32_16x16x32_bf16 v[68:71], v[144:147], v[208:211], v[68:71]
	v_mfma_f32_16x16x32_bf16 v[64:67], v[168:171], v[208:211], v[64:67]
	v_mfma_f32_16x16x32_bf16 v[116:119], v[148:151], v[180:183], v[116:119]
	v_mfma_f32_16x16x32_bf16 v[112:115], v[172:175], v[180:183], v[112:115]
	v_mfma_f32_16x16x32_bf16 v[100:103], v[148:151], v[196:199], v[100:103]
	v_mfma_f32_16x16x32_bf16 v[96:99], v[172:175], v[196:199], v[96:99]
	v_mfma_f32_16x16x32_bf16 v[84:87], v[148:151], v[204:207], v[84:87]
	v_mfma_f32_16x16x32_bf16 v[80:83], v[172:175], v[204:207], v[80:83]
	v_mfma_f32_16x16x32_bf16 v[68:71], v[148:151], v[212:215], v[68:71]
	v_mfma_f32_16x16x32_bf16 v[64:67], v[172:175], v[212:215], v[64:67]
	s_add_i32 s61, s54, s45
	s_mov_b32 m0, s61
	s_barrier
	global_load_lds_dwordx4 v[184:185], off
	s_add_i32 m0, s61, 0x2000
	s_add_i32 s61, s55, s45
	global_load_lds_dwordx4 v[216:217], off
	s_mov_b32 m0, s61
	s_nop 0
	global_load_lds_dwordx4 v[246:247], off
	s_add_i32 m0, s61, 0x2000
	s_nop 0
	global_load_lds_dwordx4 v[248:249], off
	ds_read_b128 v[176:179], v191 offset:16384
	ds_read_b128 v[180:183], v191 offset:17408
	ds_read_b128 v[192:195], v191 offset:18432
	ds_read_b128 v[196:199], v191 offset:19456
	ds_read_b128 v[200:203], v191 offset:20480
	ds_read_b128 v[204:207], v191 offset:21504
	ds_read_b128 v[208:211], v191 offset:22528
	ds_read_b128 v[212:215], v191 offset:23552
	s_waitcnt vmcnt(6)
	s_waitcnt lgkmcnt(0)
	s_barrier
; #define PG8_STAGE(bufoff, gbase, voff) do { _Pragma("unroll") for (int _i = 0; _i < 2; ++_i) \
;         __builtin_amdgcn_global_load_lds((const unsigned*)((const char*)(gbase) + (voff)[_i]), (PG8_LAS unsigned*)(lds + (bufoff) + ldsw + _i * 8192), 16, 0, 0); } while (0)
; #define PG8_LDA(dst, b, h) do { _Pragma("unroll") for (int m = 0; m < 4; ++m) _Pragma("unroll") for (int k = 0; k < 2; ++k) dst[m][k] = *(const PG8_LAS bf16x8*)(lds + PG8_SA(b, h) + aoff + m * 2048 + k * 1024); } while (0)
; #define PG8_LDB(dst, b, h) do { _Pragma("unroll") for (int n = 0; n < 2; ++n) _Pragma("unroll") for (int k = 0; k < 2; ++k) dst[n][k] = *(const PG8_LAS bf16x8*)(lds + PG8_SB(b, h) + boff + n * 2048 + k * 1024); } while (0)
; #define PG8_MMA(ai, bj, At, Bt) do { __builtin_amdgcn_s_setprio(1); _Pragma("unroll") for (int m = 0; m < 4; ++m) _Pragma("unroll") for (int n = 0; n < 2; ++n) _Pragma("unroll") for (int k = 0; k < 2; ++k) \
;         acc[ai][bj][m][n] = __builtin_amdgcn_mfma_f32_16x16x32_bf16(Bt[n][k], At[m][k], acc[ai][bj][m][n], 0, 0, 0); __builtin_amdgcn_s_setprio(0); } while (0)
; #define PG8_WAIT_V(n) asm volatile("s_waitcnt vmcnt(" #n ")" ::: "memory")
; #define PG8_WAIT_L(n) asm volatile("s_waitcnt lgkmcnt(" #n ")" ::: "memory")
; #define PG8_BAR __builtin_amdgcn_s_barrier()
; #define PG8_SCHED __builtin_amdgcn_sched_barrier(0)
; template <class Epi, class Sched, bool ALIGN_EPI = false, bool SP2 = false>
; __device__ __forceinline__ void gemm_phase(PG8_LAS unsigned char* lds, const Gemm g, const Sched& S, const Epi& E) {
;     ...
;             PG8_WAIT_V(8); PG8_WAIT_L(0); PG8_BAR; PG8_MMA(1, 0, At, B0); PG8_MMA(1, 1, At, B1); PG8_BAR; PG8_SCHED;
;             PG8_LDB(B0, 1, 0); PG8_LDB(B1, 1, 1); PG8_SCHED; PG8_LDA(At, 1, 0); PG8_STAGE(PG8_SA(0, 1), a2 + hstep, voffA);
;             PG8_WAIT_V(8); PG8_WAIT_L(0); PG8_BAR; PG8_MMA(0, 0, At, B0); PG8_MMA(0, 1, At, B1); PG8_BAR; PG8_SCHED;
	s_waitcnt lgkmcnt(0)
	v_mfma_f32_16x16x32_bf16 v[60:63], v[128:131], v[176:179], v[60:63]
	v_mfma_f32_16x16x32_bf16 v[56:59], v[136:139], v[176:179], v[56:59]
	v_mfma_f32_16x16x32_bf16 v[44:47], v[128:131], v[192:195], v[44:47]
	v_mfma_f32_16x16x32_bf16 v[40:43], v[136:139], v[192:195], v[40:43]
	v_mfma_f32_16x16x32_bf16 v[28:31], v[128:131], v[200:203], v[28:31]
	v_mfma_f32_16x16x32_bf16 v[24:27], v[136:139], v[200:203], v[24:27]
	v_mfma_f32_16x16x32_bf16 v[12:15], v[128:131], v[208:211], v[12:15]
	v_mfma_f32_16x16x32_bf16 v[8:11], v[136:139], v[208:211], v[8:11]
	v_mfma_f32_16x16x32_bf16 v[60:63], v[132:135], v[180:183], v[60:63]
	v_mfma_f32_16x16x32_bf16 v[56:59], v[140:143], v[180:183], v[56:59]
	v_mfma_f32_16x16x32_bf16 v[44:47], v[132:135], v[196:199], v[44:47]
	v_mfma_f32_16x16x32_bf16 v[40:43], v[140:143], v[196:199], v[40:43]
	v_mfma_f32_16x16x32_bf16 v[28:31], v[132:135], v[204:207], v[28:31]
	v_mfma_f32_16x16x32_bf16 v[24:27], v[140:143], v[204:207], v[24:27]
	v_mfma_f32_16x16x32_bf16 v[12:15], v[132:135], v[212:215], v[12:15]
	v_mfma_f32_16x16x32_bf16 v[8:11], v[140:143], v[212:215], v[8:11]
	v_mfma_f32_16x16x32_bf16 v[52:55], v[144:147], v[176:179], v[52:55]
	v_mfma_f32_16x16x32_bf16 v[48:51], v[168:171], v[176:179], v[48:51]
	v_mfma_f32_16x16x32_bf16 v[36:39], v[144:147], v[192:195], v[36:39]
	v_mfma_f32_16x16x32_bf16 v[32:35], v[168:171], v[192:195], v[32:35]
	v_mfma_f32_16x16x32_bf16 v[20:23], v[144:147], v[200:203], v[20:23]
	v_mfma_f32_16x16x32_bf16 v[16:19], v[168:171], v[200:203], v[16:19]
	v_mfma_f32_16x16x32_bf16 v[4:7], v[144:147], v[208:211], v[4:7]
	v_mfma_f32_16x16x32_bf16 v[0:3], v[168:171], v[208:211], v[0:3]
	v_mfma_f32_16x16x32_bf16 v[52:55], v[148:151], v[180:183], v[52:55]
	v_mfma_f32_16x16x32_bf16 v[48:51], v[172:175], v[180:183], v[48:51]
	v_mfma_f32_16x16x32_bf16 v[36:39], v[148:151], v[196:199], v[36:39]
	v_mfma_f32_16x16x32_bf16 v[32:35], v[172:175], v[196:199], v[32:35]
	v_mfma_f32_16x16x32_bf16 v[20:23], v[148:151], v[204:207], v[20:23]
	v_mfma_f32_16x16x32_bf16 v[16:19], v[172:175], v[204:207], v[16:19]
	v_mfma_f32_16x16x32_bf16 v[4:7], v[148:151], v[212:215], v[4:7]
	v_mfma_f32_16x16x32_bf16 v[0:3], v[172:175], v[212:215], v[0:3]
	s_barrier
	s_add_i32 s61, 0, 0x18000
	s_add_i32 s62, 0, 0x1c000
	v_add_u32_e32 v140, s61, v187
	v_add_u32_e32 v172, s62, v187
	ds_read_b128 v[128:131], v140
	ds_read_b128 v[132:135], v140 offset:1024
	ds_read_b128 v[136:139], v140 offset:2048
	ds_read_b128 v[140:143], v140 offset:3072
	ds_read_b128 v[144:147], v172
	ds_read_b128 v[148:151], v172 offset:1024
	ds_read_b128 v[168:171], v172 offset:2048
	ds_read_b128 v[172:175], v172 offset:3072
	s_mov_b32 m0, s31
	s_nop 0
	global_load_lds_dwordx4 v[218:219], off
	s_mov_b32 m0, s46
	s_nop 0
	global_load_lds_dwordx4 v[220:221], off
	s_add_u32 s38, s38, 0x80000
	s_addc_u32 s39, s39, 0
	s_mov_b32 m0, s47
	v_lshl_add_u64 v[222:223], s[38:39], 0, v[152:153]
	global_load_lds_dwordx4 v[222:223], off
	v_lshl_add_u64 v[222:223], s[38:39], 0, v[156:157]
	s_mov_b32 m0, s48
	s_nop 0
	global_load_lds_dwordx4 v[222:223], off
	ds_read_b128 v[176:179], v191 offset:32768
	ds_read_b128 v[180:183], v191 offset:33792
	ds_read_b128 v[192:195], v191 offset:34816
	ds_read_b128 v[196:199], v191 offset:35840
	ds_read_b128 v[200:203], v191 offset:36864
	ds_read_b128 v[204:207], v191 offset:37888
	ds_read_b128 v[208:211], v191 offset:38912
	ds_read_b128 v[212:215], v191 offset:39936
	s_waitcnt vmcnt(8)
	s_waitcnt lgkmcnt(0)
	s_barrier
; #define PG8_STAGE(bufoff, gbase, voff) do { _Pragma("unroll") for (int _i = 0; _i < 2; ++_i) \
;         __builtin_amdgcn_global_load_lds((const unsigned*)((const char*)(gbase) + (voff)[_i]), (PG8_LAS unsigned*)(lds + (bufoff) + ldsw + _i * 8192), 16, 0, 0); } while (0)
; #define PG8_LDA(dst, b, h) do { _Pragma("unroll") for (int m = 0; m < 4; ++m) _Pragma("unroll") for (int k = 0; k < 2; ++k) dst[m][k] = *(const PG8_LAS bf16x8*)(lds + PG8_SA(b, h) + aoff + m * 2048 + k * 1024); } while (0)
; #define PG8_MMA(ai, bj, At, Bt) do { __builtin_amdgcn_s_setprio(1); _Pragma("unroll") for (int m = 0; m < 4; ++m) _Pragma("unroll") for (int n = 0; n < 2; ++n) _Pragma("unroll") for (int k = 0; k < 2; ++k) \
;         acc[ai][bj][m][n] = __builtin_amdgcn_mfma_f32_16x16x32_bf16(Bt[n][k], At[m][k], acc[ai][bj][m][n], 0, 0, 0); __builtin_amdgcn_s_setprio(0); } while (0)
; #define PG8_WAIT_V(n) asm volatile("s_waitcnt vmcnt(" #n ")" ::: "memory")
; #define PG8_WAIT_L(n) asm volatile("s_waitcnt lgkmcnt(" #n ")" ::: "memory")
; #define PG8_BAR __builtin_amdgcn_s_barrier()
; #define PG8_SCHED __builtin_amdgcn_sched_barrier(0)
; template <class Epi, class Sched, bool ALIGN_EPI = false, bool SP2 = false>
; __device__ __forceinline__ void gemm_phase(PG8_LAS unsigned char* lds, const Gemm g, const Sched& S, const Epi& E) {
;     ...
;         for (int t = 0; t < nt; t += 2) {
;     ...
;             PG8_WAIT_V(8); PG8_WAIT_L(0); PG8_BAR; PG8_MMA(0, 0, At, B0); PG8_MMA(0, 1, At, B1); PG8_BAR; PG8_SCHED;
;             PG8_LDA(At, 1, 1); PG8_STAGE(PG8_SB(1, 0), b3, voffB); PG8_STAGE(PG8_SB(1, 1), b3 + hstep, voffB); PG8_STAGE(PG8_SA(1, 0), a3, voffA);
;             PG8_WAIT_V(8); PG8_WAIT_L(0); PG8_BAR; PG8_MMA(1, 0, At, B0); PG8_MMA(1, 1, At, B1); PG8_BAR; PG8_SCHED;
	s_waitcnt lgkmcnt(0)
	v_mfma_f32_16x16x32_bf16 v[124:127], v[128:131], v[176:179], v[124:127]
	v_mfma_f32_16x16x32_bf16 v[120:123], v[136:139], v[176:179], v[120:123]
	s_add_u32 s36, s36, 0x80080
	v_mfma_f32_16x16x32_bf16 v[108:111], v[128:131], v[192:195], v[108:111]
	v_mfma_f32_16x16x32_bf16 v[104:107], v[136:139], v[192:195], v[104:107]
	s_addc_u32 s37, s37, 0
	v_mfma_f32_16x16x32_bf16 v[92:95], v[128:131], v[200:203], v[92:95]
	v_mfma_f32_16x16x32_bf16 v[88:91], v[136:139], v[200:203], v[88:91]
	v_lshl_add_u64 v[184:185], v[184:185], 0, s[10:11]
	v_mfma_f32_16x16x32_bf16 v[76:79], v[128:131], v[208:211], v[76:79]
	v_mfma_f32_16x16x32_bf16 v[72:75], v[136:139], v[208:211], v[72:75]
	v_lshl_add_u64 v[216:217], v[216:217], 0, s[10:11]
	v_mfma_f32_16x16x32_bf16 v[124:127], v[132:135], v[180:183], v[124:127]
	v_mfma_f32_16x16x32_bf16 v[120:123], v[140:143], v[180:183], v[120:123]
	v_lshl_add_u64 v[246:247], s[36:37], 0, v[154:155]
	v_mfma_f32_16x16x32_bf16 v[108:111], v[132:135], v[196:199], v[108:111]
	v_mfma_f32_16x16x32_bf16 v[104:107], v[140:143], v[196:199], v[104:107]
	v_lshl_add_u64 v[248:249], s[36:37], 0, v[158:159]
	v_mfma_f32_16x16x32_bf16 v[92:95], v[132:135], v[204:207], v[92:95]
	v_mfma_f32_16x16x32_bf16 v[88:91], v[140:143], v[204:207], v[88:91]
	v_lshl_add_u64 v[250:251], v[218:219], 0, s[10:11]
	v_mfma_f32_16x16x32_bf16 v[76:79], v[132:135], v[212:215], v[76:79]
	v_mfma_f32_16x16x32_bf16 v[72:75], v[140:143], v[212:215], v[72:75]
	v_lshl_add_u64 v[252:253], v[220:221], 0, s[10:11]
	v_mfma_f32_16x16x32_bf16 v[116:119], v[144:147], v[176:179], v[116:119]
	v_mfma_f32_16x16x32_bf16 v[112:115], v[168:171], v[176:179], v[112:115]
	v_mfma_f32_16x16x32_bf16 v[100:103], v[144:147], v[192:195], v[100:103]
	v_mfma_f32_16x16x32_bf16 v[96:99], v[168:171], v[192:195], v[96:99]
	v_mfma_f32_16x16x32_bf16 v[84:87], v[144:147], v[200:203], v[84:87]
	v_mfma_f32_16x16x32_bf16 v[80:83], v[168:171], v[200:203], v[80:83]
	v_mfma_f32_16x16x32_bf16 v[68:71], v[144:147], v[208:211], v[68:71]
	v_mfma_f32_16x16x32_bf16 v[64:67], v[168:171], v[208:211], v[64:67]
	v_mfma_f32_16x16x32_bf16 v[116:119], v[148:151], v[180:183], v[116:119]
	v_mfma_f32_16x16x32_bf16 v[112:115], v[172:175], v[180:183], v[112:115]
	v_mfma_f32_16x16x32_bf16 v[100:103], v[148:151], v[196:199], v[100:103]
	v_mfma_f32_16x16x32_bf16 v[96:99], v[172:175], v[196:199], v[96:99]
	v_mfma_f32_16x16x32_bf16 v[84:87], v[148:151], v[204:207], v[84:87]
	v_mfma_f32_16x16x32_bf16 v[80:83], v[172:175], v[204:207], v[80:83]
	v_mfma_f32_16x16x32_bf16 v[68:71], v[148:151], v[212:215], v[68:71]
	v_mfma_f32_16x16x32_bf16 v[64:67], v[172:175], v[212:215], v[64:67]
	s_add_i32 s38, s61, s45
	s_mov_b32 m0, s38
	s_barrier
	global_load_lds_dwordx4 v[184:185], off
	s_add_i32 m0, s38, 0x2000
	s_add_i32 s38, s62, s45
	global_load_lds_dwordx4 v[216:217], off
	s_mov_b32 m0, s38
	s_nop 0
	global_load_lds_dwordx4 v[246:247], off
	s_add_i32 m0, s38, 0x2000
	s_nop 0
	global_load_lds_dwordx4 v[248:249], off
	ds_read_b128 v[176:179], v191 offset:49152
	ds_read_b128 v[180:183], v191 offset:50176
	ds_read_b128 v[192:195], v191 offset:51200
	ds_read_b128 v[196:199], v191 offset:52224
	ds_read_b128 v[200:203], v191 offset:53248
	ds_read_b128 v[204:207], v191 offset:54272
	ds_read_b128 v[208:211], v191 offset:55296
	ds_read_b128 v[212:215], v191 offset:56320
	s_waitcnt vmcnt(6)
	s_waitcnt lgkmcnt(0)
	s_barrier
	s_waitcnt lgkmcnt(0)
	v_mfma_f32_16x16x32_bf16 v[60:63], v[128:131], v[176:179], v[60:63]
	v_mfma_f32_16x16x32_bf16 v[56:59], v[136:139], v[176:179], v[56:59]
	v_mfma_f32_16x16x32_bf16 v[44:47], v[128:131], v[192:195], v[44:47]
	v_mfma_f32_16x16x32_bf16 v[40:43], v[136:139], v[192:195], v[40:43]
	v_mfma_f32_16x16x32_bf16 v[28:31], v[128:131], v[200:203], v[28:31]
	v_mfma_f32_16x16x32_bf16 v[24:27], v[136:139], v[200:203], v[24:27]
	v_mfma_f32_16x16x32_bf16 v[12:15], v[128:131], v[208:211], v[12:15]
	v_mfma_f32_16x16x32_bf16 v[8:11], v[136:139], v[208:211], v[8:11]
	v_mfma_f32_16x16x32_bf16 v[60:63], v[132:135], v[180:183], v[60:63]
	v_mfma_f32_16x16x32_bf16 v[56:59], v[140:143], v[180:183], v[56:59]
	v_mfma_f32_16x16x32_bf16 v[44:47], v[132:135], v[196:199], v[44:47]
	v_mfma_f32_16x16x32_bf16 v[40:43], v[140:143], v[196:199], v[40:43]
	v_mfma_f32_16x16x32_bf16 v[28:31], v[132:135], v[204:207], v[28:31]
	v_mfma_f32_16x16x32_bf16 v[24:27], v[140:143], v[204:207], v[24:27]
	v_mfma_f32_16x16x32_bf16 v[12:15], v[132:135], v[212:215], v[12:15]
	v_mfma_f32_16x16x32_bf16 v[8:11], v[140:143], v[212:215], v[8:11]
	v_mfma_f32_16x16x32_bf16 v[52:55], v[144:147], v[176:179], v[52:55]
	v_mfma_f32_16x16x32_bf16 v[48:51], v[168:171], v[176:179], v[48:51]
	v_mfma_f32_16x16x32_bf16 v[36:39], v[144:147], v[192:195], v[36:39]
	v_mfma_f32_16x16x32_bf16 v[32:35], v[168:171], v[192:195], v[32:35]
	s_add_i32 s60, s60, 2
	v_mfma_f32_16x16x32_bf16 v[20:23], v[144:147], v[200:203], v[20:23]
	v_mfma_f32_16x16x32_bf16 v[16:19], v[168:171], v[200:203], v[16:19]
	s_add_u32 s34, s34, 0x100
	v_mfma_f32_16x16x32_bf16 v[4:7], v[144:147], v[208:211], v[4:7]
	v_mfma_f32_16x16x32_bf16 v[0:3], v[168:171], v[208:211], v[0:3]
	s_addc_u32 s35, s35, 0
	v_mfma_f32_16x16x32_bf16 v[52:55], v[148:151], v[180:183], v[52:55]
	v_mfma_f32_16x16x32_bf16 v[48:51], v[172:175], v[180:183], v[48:51]
	s_add_u32 s58, s58, 0x100
	v_mfma_f32_16x16x32_bf16 v[36:39], v[148:151], v[196:199], v[36:39]
	v_mfma_f32_16x16x32_bf16 v[32:35], v[172:175], v[196:199], v[32:35]
	s_addc_u32 s59, s59, 0
	v_mfma_f32_16x16x32_bf16 v[20:23], v[148:151], v[204:207], v[20:23]
	v_mfma_f32_16x16x32_bf16 v[16:19], v[172:175], v[204:207], v[16:19]
	v_mfma_f32_16x16x32_bf16 v[4:7], v[148:151], v[212:215], v[4:7]
	v_mfma_f32_16x16x32_bf16 v[0:3], v[172:175], v[212:215], v[0:3]
	s_barrier
	s_cmp_gt_u32 s60, 29
	s_cbranch_scc0 .LBB0_621
	s_and_b64 vcc, exec, s[12:13]
	s_cbranch_vccz .LBB0_624
	s_barrier

; #define PG8_STAGE(bufoff, gbase, voff) do { _Pragma("unroll") for (int _i = 0; _i < 2; ++_i) \
;         __builtin_amdgcn_global_load_lds((const unsigned*)((const char*)(gbase) + (voff)[_i]), (PG8_LAS unsigned*)(lds + (bufoff) + ldsw + _i * 8192), 16, 0, 0); } while (0)
; #define PG8_LDA(dst, b, h) do { _Pragma("unroll") for (int m = 0; m < 4; ++m) _Pragma("unroll") for (int k = 0; k < 2; ++k) dst[m][k] = *(const PG8_LAS bf16x8*)(lds + PG8_SA(b, h) + aoff + m * 2048 + k * 1024); } while (0)
; #define PG8_LDB(dst, b, h) do { _Pragma("unroll") for (int n = 0; n < 2; ++n) _Pragma("unroll") for (int k = 0; k < 2; ++k) dst[n][k] = *(const PG8_LAS bf16x8*)(lds + PG8_SB(b, h) + boff + n * 2048 + k * 1024); } while (0)
; #define PG8_MMA(ai, bj, At, Bt) do { __builtin_amdgcn_s_setprio(1); _Pragma("unroll") for (int m = 0; m < 4; ++m) _Pragma("unroll") for (int n = 0; n < 2; ++n) _Pragma("unroll") for (int k = 0; k < 2; ++k) \
;         acc[ai][bj][m][n] = __builtin_amdgcn_mfma_f32_16x16x32_bf16(Bt[n][k], At[m][k], acc[ai][bj][m][n], 0, 0, 0); __builtin_amdgcn_s_setprio(0); } while (0)
; #define PG8_WAIT_V(n) asm volatile("s_waitcnt vmcnt(" #n ")" ::: "memory")
; #define PG8_WAIT_L(n) asm volatile("s_waitcnt lgkmcnt(" #n ")" ::: "memory")
; #define PG8_BAR __builtin_amdgcn_s_barrier()
; #define PG8_SCHED __builtin_amdgcn_sched_barrier(0)
; template <class Epi, class Sched, bool ALIGN_EPI = false, bool SP2 = false>
; __device__ __forceinline__ void gemm_phase(PG8_LAS unsigned char* lds, const Gemm g, const Sched& S, const Epi& E) {
;     ...
;             PG8_LDB(B0, 0, 0); PG8_LDB(B1, 0, 1); PG8_SCHED; PG8_LDA(At, 0, 0); PG8_STAGE(PG8_SA(1, 1), a1 + hstep, voffA);
;             PG8_WAIT_V(8); PG8_WAIT_L(0); PG8_BAR; PG8_MMA(0, 0, At, B0); PG8_MMA(0, 1, At, B1); PG8_BAR; PG8_SCHED;
;             PG8_LDA(At, 0, 1); PG8_STAGE(PG8_SB(0, 0), b2, voffB); PG8_STAGE(PG8_SB(0, 1), b2 + hstep, voffB); PG8_STAGE(PG8_SA(0, 0), a2, voffA);
;             PG8_WAIT_V(8); PG8_WAIT_L(0); PG8_BAR; PG8_MMA(1, 0, At, B0); PG8_MMA(1, 1, At, B1); PG8_BAR; PG8_SCHED;
.LBB0_705:
	ds_read_b128 v[144:147], v151
	ds_read_b128 v[156:159], v151 offset:1024
	ds_read_b128 v[160:163], v151 offset:2048
	ds_read_b128 v[164:167], v151 offset:3072
	ds_read_b128 v[168:171], v152
	ds_read_b128 v[172:175], v152 offset:1024
	ds_read_b128 v[176:179], v152 offset:2048
	ds_read_b128 v[180:183], v152 offset:3072
	s_mov_b32 m0, s48
	s_nop 0
	global_load_lds_dwordx4 v[250:251], off
	s_mov_b32 m0, s49
	s_nop 0
	global_load_lds_dwordx4 v[252:253], off
	s_add_u32 s30, s28, 0xfff80080
	s_addc_u32 s31, s29, -1
	s_cmp_eq_u32 s60, 28
	s_cselect_b32 s35, s15, s31
	s_cselect_b32 s34, s56, s30
	s_cselect_b32 s31, s13, s59
	s_cselect_b32 s30, s57, s58
	v_lshl_add_u64 v[216:217], s[28:29], 0, v[136:137]
	s_add_i32 m0, s25, 0xc000
	s_nop 0
	global_load_lds_dwordx4 v[216:217], off
	v_lshl_add_u64 v[216:217], s[28:29], 0, v[138:139]
	s_add_i32 m0, s25, 0xe000
	s_nop 0
	global_load_lds_dwordx4 v[216:217], off
	ds_read_b128 v[184:187], v153
	ds_read_b128 v[188:191], v153 offset:1024
	ds_read_b128 v[192:195], v153 offset:2048
	ds_read_b128 v[196:199], v153 offset:3072
	ds_read_b128 v[200:203], v153 offset:4096
	ds_read_b128 v[204:207], v153 offset:5120
	ds_read_b128 v[208:211], v153 offset:6144
	ds_read_b128 v[212:215], v153 offset:7168
	s_waitcnt vmcnt(8)
	s_waitcnt lgkmcnt(0)
	s_barrier
	s_waitcnt lgkmcnt(0)
	v_mfma_f32_16x16x32_bf16 v[116:119], v[144:147], v[184:187], v[116:119]
	v_mfma_f32_16x16x32_bf16 v[112:115], v[160:163], v[184:187], v[112:115]
	s_add_u32 s62, s30, 0x80000
	v_mfma_f32_16x16x32_bf16 v[100:103], v[144:147], v[192:195], v[100:103]
	v_mfma_f32_16x16x32_bf16 v[96:99], v[160:163], v[192:195], v[96:99]
	s_addc_u32 s63, s31, 0
	v_mfma_f32_16x16x32_bf16 v[84:87], v[144:147], v[200:203], v[84:87]
	v_mfma_f32_16x16x32_bf16 v[80:83], v[160:163], v[200:203], v[80:83]
	v_lshl_add_u64 v[216:217], s[30:31], 0, v[132:133]
	v_mfma_f32_16x16x32_bf16 v[72:75], v[144:147], v[208:211], v[72:75]
	v_mfma_f32_16x16x32_bf16 v[68:71], v[160:163], v[208:211], v[68:71]
	v_lshl_add_u64 v[218:219], s[30:31], 0, v[128:129]
	v_mfma_f32_16x16x32_bf16 v[116:119], v[156:159], v[188:191], v[116:119]
	v_mfma_f32_16x16x32_bf16 v[112:115], v[164:167], v[188:191], v[112:115]
	v_lshl_add_u64 v[246:247], s[62:63], 0, v[132:133]
	v_mfma_f32_16x16x32_bf16 v[100:103], v[156:159], v[196:199], v[100:103]
	v_mfma_f32_16x16x32_bf16 v[96:99], v[164:167], v[196:199], v[96:99]
	v_lshl_add_u64 v[222:223], s[34:35], 0, v[130:131]
	v_mfma_f32_16x16x32_bf16 v[84:87], v[156:159], v[204:207], v[84:87]
	v_mfma_f32_16x16x32_bf16 v[80:83], v[164:167], v[204:207], v[80:83]
	v_lshl_add_u64 v[248:249], s[62:63], 0, v[128:129]
	v_mfma_f32_16x16x32_bf16 v[72:75], v[156:159], v[212:215], v[72:75]
	v_mfma_f32_16x16x32_bf16 v[68:71], v[164:167], v[212:215], v[68:71]
	v_lshl_add_u64 v[220:221], s[34:35], 0, v[134:135]
	v_mfma_f32_16x16x32_bf16 v[124:127], v[168:171], v[184:187], v[124:127]
	v_mfma_f32_16x16x32_bf16 v[120:123], v[176:179], v[184:187], v[120:123]
	v_mfma_f32_16x16x32_bf16 v[108:111], v[168:171], v[192:195], v[108:111]
	v_mfma_f32_16x16x32_bf16 v[104:107], v[176:179], v[192:195], v[104:107]
	v_mfma_f32_16x16x32_bf16 v[92:95], v[168:171], v[200:203], v[92:95]
	v_mfma_f32_16x16x32_bf16 v[88:91], v[176:179], v[200:203], v[88:91]
	v_mfma_f32_16x16x32_bf16 v[76:79], v[168:171], v[208:211], v[76:79]
	v_mfma_f32_16x16x32_bf16 v[64:67], v[176:179], v[208:211], v[64:67]
	v_mfma_f32_16x16x32_bf16 v[124:127], v[172:175], v[188:191], v[124:127]
	v_mfma_f32_16x16x32_bf16 v[120:123], v[180:183], v[188:191], v[120:123]
	v_mfma_f32_16x16x32_bf16 v[108:111], v[172:175], v[196:199], v[108:111]
	v_mfma_f32_16x16x32_bf16 v[104:107], v[180:183], v[196:199], v[104:107]
	v_mfma_f32_16x16x32_bf16 v[92:95], v[172:175], v[204:207], v[92:95]
	v_mfma_f32_16x16x32_bf16 v[88:91], v[180:183], v[204:207], v[88:91]
	v_mfma_f32_16x16x32_bf16 v[76:79], v[172:175], v[212:215], v[76:79]
	v_mfma_f32_16x16x32_bf16 v[64:67], v[180:183], v[212:215], v[64:67]
	s_add_i32 s61, s52, s42
	s_mov_b32 m0, s61
	s_barrier
	global_load_lds_dwordx4 v[216:217], off
	s_add_i32 m0, s61, 0x2000
	s_add_i32 s61, s53, s42
	global_load_lds_dwordx4 v[218:219], off
	s_mov_b32 m0, s61
	s_nop 0
	global_load_lds_dwordx4 v[246:247], off
	s_add_i32 m0, s61, 0x2000
	s_nop 0
	global_load_lds_dwordx4 v[248:249], off
	ds_read_b128 v[184:187], v153 offset:16384
	ds_read_b128 v[188:191], v153 offset:17408
	ds_read_b128 v[192:195], v153 offset:18432
	ds_read_b128 v[196:199], v153 offset:19456
	ds_read_b128 v[200:203], v153 offset:20480
	ds_read_b128 v[204:207], v153 offset:21504
	ds_read_b128 v[208:211], v153 offset:22528
	ds_read_b128 v[212:215], v153 offset:23552
	s_waitcnt vmcnt(6)
	s_waitcnt lgkmcnt(0)
	s_barrier
; #define PG8_STAGE(bufoff, gbase, voff) do { _Pragma("unroll") for (int _i = 0; _i < 2; ++_i) \
;         __builtin_amdgcn_global_load_lds((const unsigned*)((const char*)(gbase) + (voff)[_i]), (PG8_LAS unsigned*)(lds + (bufoff) + ldsw + _i * 8192), 16, 0, 0); } while (0)
; #define PG8_LDA(dst, b, h) do { _Pragma("unroll") for (int m = 0; m < 4; ++m) _Pragma("unroll") for (int k = 0; k < 2; ++k) dst[m][k] = *(const PG8_LAS bf16x8*)(lds + PG8_SA(b, h) + aoff + m * 2048 + k * 1024); } while (0)
; #define PG8_LDB(dst, b, h) do { _Pragma("unroll") for (int n = 0; n < 2; ++n) _Pragma("unroll") for (int k = 0; k < 2; ++k) dst[n][k] = *(const PG8_LAS bf16x8*)(lds + PG8_SB(b, h) + boff + n * 2048 + k * 1024); } while (0)
; #define PG8_MMA(ai, bj, At, Bt) do { __builtin_amdgcn_s_setprio(1); _Pragma("unroll") for (int m = 0; m < 4; ++m) _Pragma("unroll") for (int n = 0; n < 2; ++n) _Pragma("unroll") for (int k = 0; k < 2; ++k) \
;         acc[ai][bj][m][n] = __builtin_amdgcn_mfma_f32_16x16x32_bf16(Bt[n][k], At[m][k], acc[ai][bj][m][n], 0, 0, 0); __builtin_amdgcn_s_setprio(0); } while (0)
; #define PG8_WAIT_V(n) asm volatile("s_waitcnt vmcnt(" #n ")" ::: "memory")
; #define PG8_WAIT_L(n) asm volatile("s_waitcnt lgkmcnt(" #n ")" ::: "memory")
; #define PG8_BAR __builtin_amdgcn_s_barrier()
; #define PG8_SCHED __builtin_amdgcn_sched_barrier(0)
; template <class Epi, class Sched, bool ALIGN_EPI = false, bool SP2 = false>
; __device__ __forceinline__ void gemm_phase(PG8_LAS unsigned char* lds, const Gemm g, const Sched& S, const Epi& E) {
;     ...
;             PG8_WAIT_V(8); PG8_WAIT_L(0); PG8_BAR; PG8_MMA(1, 0, At, B0); PG8_MMA(1, 1, At, B1); PG8_BAR; PG8_SCHED;
;             PG8_LDB(B0, 1, 0); PG8_LDB(B1, 1, 1); PG8_SCHED; PG8_LDA(At, 1, 0); PG8_STAGE(PG8_SA(0, 1), a2 + hstep, voffA);
;             PG8_WAIT_V(8); PG8_WAIT_L(0); PG8_BAR; PG8_MMA(0, 0, At, B0); PG8_MMA(0, 1, At, B1); PG8_BAR; PG8_SCHED;
	s_waitcnt lgkmcnt(0)
	v_mfma_f32_16x16x32_bf16 v[56:59], v[144:147], v[184:187], v[56:59]
	v_mfma_f32_16x16x32_bf16 v[52:55], v[160:163], v[184:187], v[52:55]
	v_mfma_f32_16x16x32_bf16 v[40:43], v[144:147], v[192:195], v[40:43]
	v_mfma_f32_16x16x32_bf16 v[36:39], v[160:163], v[192:195], v[36:39]
	v_mfma_f32_16x16x32_bf16 v[24:27], v[144:147], v[200:203], v[24:27]
	v_mfma_f32_16x16x32_bf16 v[20:23], v[160:163], v[200:203], v[20:23]
	v_mfma_f32_16x16x32_bf16 v[8:11], v[144:147], v[208:211], v[8:11]
	v_mfma_f32_16x16x32_bf16 v[0:3], v[160:163], v[208:211], v[0:3]
	v_mfma_f32_16x16x32_bf16 v[56:59], v[156:159], v[188:191], v[56:59]
	v_mfma_f32_16x16x32_bf16 v[52:55], v[164:167], v[188:191], v[52:55]
	v_mfma_f32_16x16x32_bf16 v[40:43], v[156:159], v[196:199], v[40:43]
	v_mfma_f32_16x16x32_bf16 v[36:39], v[164:167], v[196:199], v[36:39]
	v_mfma_f32_16x16x32_bf16 v[24:27], v[156:159], v[204:207], v[24:27]
	v_mfma_f32_16x16x32_bf16 v[20:23], v[164:167], v[204:207], v[20:23]
	v_mfma_f32_16x16x32_bf16 v[8:11], v[156:159], v[212:215], v[8:11]
	v_mfma_f32_16x16x32_bf16 v[0:3], v[164:167], v[212:215], v[0:3]
	v_mfma_f32_16x16x32_bf16 v[60:63], v[168:171], v[184:187], v[60:63]
	v_mfma_f32_16x16x32_bf16 v[48:51], v[176:179], v[184:187], v[48:51]
	v_mfma_f32_16x16x32_bf16 v[44:47], v[168:171], v[192:195], v[44:47]
	v_mfma_f32_16x16x32_bf16 v[32:35], v[176:179], v[192:195], v[32:35]
	v_mfma_f32_16x16x32_bf16 v[28:31], v[168:171], v[200:203], v[28:31]
	v_mfma_f32_16x16x32_bf16 v[16:19], v[176:179], v[200:203], v[16:19]
	v_mfma_f32_16x16x32_bf16 v[12:15], v[168:171], v[208:211], v[12:15]
	v_mfma_f32_16x16x32_bf16 v[4:7], v[176:179], v[208:211], v[4:7]
	v_mfma_f32_16x16x32_bf16 v[60:63], v[172:175], v[188:191], v[60:63]
	v_mfma_f32_16x16x32_bf16 v[48:51], v[180:183], v[188:191], v[48:51]
	v_mfma_f32_16x16x32_bf16 v[44:47], v[172:175], v[196:199], v[44:47]
	v_mfma_f32_16x16x32_bf16 v[32:35], v[180:183], v[196:199], v[32:35]
	v_mfma_f32_16x16x32_bf16 v[28:31], v[172:175], v[204:207], v[28:31]
	v_mfma_f32_16x16x32_bf16 v[16:19], v[180:183], v[204:207], v[16:19]
	v_mfma_f32_16x16x32_bf16 v[12:15], v[172:175], v[212:215], v[12:15]
	v_mfma_f32_16x16x32_bf16 v[4:7], v[180:183], v[212:215], v[4:7]
	s_barrier
	s_add_i32 s61, 0, 0x18000
	v_add_u32_e32 v155, s61, v149
	s_add_i32 s62, 0, 0x1c000
	ds_read_b128 v[144:147], v155
	ds_read_b128 v[156:159], v155 offset:1024
	ds_read_b128 v[160:163], v155 offset:2048
	ds_read_b128 v[164:167], v155 offset:3072
	v_add_u32_e32 v155, s62, v149
	ds_read_b128 v[168:171], v155
	ds_read_b128 v[172:175], v155 offset:1024
	ds_read_b128 v[176:179], v155 offset:2048
	ds_read_b128 v[180:183], v155 offset:3072
	s_mov_b32 m0, s25
	s_nop 0
	global_load_lds_dwordx4 v[220:221], off
	s_mov_b32 m0, s45
	s_nop 0
	global_load_lds_dwordx4 v[222:223], off
	s_add_u32 s34, s34, 0x80000
	s_addc_u32 s35, s35, 0
	s_mov_b32 m0, s46
	v_lshl_add_u64 v[224:225], s[34:35], 0, v[134:135]
	global_load_lds_dwordx4 v[224:225], off
	v_lshl_add_u64 v[224:225], s[34:35], 0, v[130:131]
	s_mov_b32 m0, s47
	s_nop 0
	global_load_lds_dwordx4 v[224:225], off
	ds_read_b128 v[184:187], v153 offset:32768
	ds_read_b128 v[188:191], v153 offset:33792
	ds_read_b128 v[192:195], v153 offset:34816
	ds_read_b128 v[196:199], v153 offset:35840
	ds_read_b128 v[200:203], v153 offset:36864
	ds_read_b128 v[204:207], v153 offset:37888
	ds_read_b128 v[208:211], v153 offset:38912
	ds_read_b128 v[212:215], v153 offset:39936
	s_waitcnt vmcnt(8)
	s_waitcnt lgkmcnt(0)
	s_barrier
; #define PG8_STAGE(bufoff, gbase, voff) do { _Pragma("unroll") for (int _i = 0; _i < 2; ++_i) \
;         __builtin_amdgcn_global_load_lds((const unsigned*)((const char*)(gbase) + (voff)[_i]), (PG8_LAS unsigned*)(lds + (bufoff) + ldsw + _i * 8192), 16, 0, 0); } while (0)
; #define PG8_LDA(dst, b, h) do { _Pragma("unroll") for (int m = 0; m < 4; ++m) _Pragma("unroll") for (int k = 0; k < 2; ++k) dst[m][k] = *(const PG8_LAS bf16x8*)(lds + PG8_SA(b, h) + aoff + m * 2048 + k * 1024); } while (0)
; #define PG8_MMA(ai, bj, At, Bt) do { __builtin_amdgcn_s_setprio(1); _Pragma("unroll") for (int m = 0; m < 4; ++m) _Pragma("unroll") for (int n = 0; n < 2; ++n) _Pragma("unroll") for (int k = 0; k < 2; ++k) \
;         acc[ai][bj][m][n] = __builtin_amdgcn_mfma_f32_16x16x32_bf16(Bt[n][k], At[m][k], acc[ai][bj][m][n], 0, 0, 0); __builtin_amdgcn_s_setprio(0); } while (0)
; #define PG8_WAIT_V(n) asm volatile("s_waitcnt vmcnt(" #n ")" ::: "memory")
; #define PG8_WAIT_L(n) asm volatile("s_waitcnt lgkmcnt(" #n ")" ::: "memory")
; #define PG8_BAR __builtin_amdgcn_s_barrier()
; #define PG8_SCHED __builtin_amdgcn_sched_barrier(0)
; template <class Epi, class Sched, bool ALIGN_EPI = false, bool SP2 = false>
; __device__ __forceinline__ void gemm_phase(PG8_LAS unsigned char* lds, const Gemm g, const Sched& S, const Epi& E) {
;     ...
;         for (int t = 0; t < nt; t += 2) {
;     ...
;             PG8_WAIT_V(8); PG8_WAIT_L(0); PG8_BAR; PG8_MMA(0, 0, At, B0); PG8_MMA(0, 1, At, B1); PG8_BAR; PG8_SCHED;
;             PG8_LDA(At, 1, 1); PG8_STAGE(PG8_SB(1, 0), b3, voffB); PG8_STAGE(PG8_SB(1, 1), b3 + hstep, voffB); PG8_STAGE(PG8_SA(1, 0), a3, voffA);
;             PG8_WAIT_V(8); PG8_WAIT_L(0); PG8_BAR; PG8_MMA(1, 0, At, B0); PG8_MMA(1, 1, At, B1); PG8_BAR; PG8_SCHED;
	s_waitcnt lgkmcnt(0)
	v_mfma_f32_16x16x32_bf16 v[116:119], v[144:147], v[184:187], v[116:119]
	v_mfma_f32_16x16x32_bf16 v[112:115], v[160:163], v[184:187], v[112:115]
	s_add_u32 s30, s30, 0x80080
	v_mfma_f32_16x16x32_bf16 v[100:103], v[144:147], v[192:195], v[100:103]
	v_mfma_f32_16x16x32_bf16 v[96:99], v[160:163], v[192:195], v[96:99]
	s_addc_u32 s31, s31, 0
	v_mfma_f32_16x16x32_bf16 v[84:87], v[144:147], v[200:203], v[84:87]
	v_mfma_f32_16x16x32_bf16 v[80:83], v[160:163], v[200:203], v[80:83]
	v_lshl_add_u64 v[216:217], v[216:217], 0, s[8:9]
	v_mfma_f32_16x16x32_bf16 v[72:75], v[144:147], v[208:211], v[72:75]
	v_mfma_f32_16x16x32_bf16 v[68:71], v[160:163], v[208:211], v[68:71]
	v_lshl_add_u64 v[218:219], v[218:219], 0, s[8:9]
	v_mfma_f32_16x16x32_bf16 v[116:119], v[156:159], v[188:191], v[116:119]
	v_mfma_f32_16x16x32_bf16 v[112:115], v[164:167], v[188:191], v[112:115]
	v_lshl_add_u64 v[246:247], s[30:31], 0, v[132:133]
	v_mfma_f32_16x16x32_bf16 v[100:103], v[156:159], v[196:199], v[100:103]
	v_mfma_f32_16x16x32_bf16 v[96:99], v[164:167], v[196:199], v[96:99]
	v_lshl_add_u64 v[248:249], s[30:31], 0, v[128:129]
	v_mfma_f32_16x16x32_bf16 v[84:87], v[156:159], v[204:207], v[84:87]
	v_mfma_f32_16x16x32_bf16 v[80:83], v[164:167], v[204:207], v[80:83]
	v_lshl_add_u64 v[250:251], v[220:221], 0, s[8:9]
	v_mfma_f32_16x16x32_bf16 v[72:75], v[156:159], v[212:215], v[72:75]
	v_mfma_f32_16x16x32_bf16 v[68:71], v[164:167], v[212:215], v[68:71]
	v_lshl_add_u64 v[252:253], v[222:223], 0, s[8:9]
	v_mfma_f32_16x16x32_bf16 v[124:127], v[168:171], v[184:187], v[124:127]
	v_mfma_f32_16x16x32_bf16 v[120:123], v[176:179], v[184:187], v[120:123]
	v_mfma_f32_16x16x32_bf16 v[108:111], v[168:171], v[192:195], v[108:111]
	v_mfma_f32_16x16x32_bf16 v[104:107], v[176:179], v[192:195], v[104:107]
	v_mfma_f32_16x16x32_bf16 v[92:95], v[168:171], v[200:203], v[92:95]
	v_mfma_f32_16x16x32_bf16 v[88:91], v[176:179], v[200:203], v[88:91]
	v_mfma_f32_16x16x32_bf16 v[76:79], v[168:171], v[208:211], v[76:79]
	v_mfma_f32_16x16x32_bf16 v[64:67], v[176:179], v[208:211], v[64:67]
	v_mfma_f32_16x16x32_bf16 v[124:127], v[172:175], v[188:191], v[124:127]
	v_mfma_f32_16x16x32_bf16 v[120:123], v[180:183], v[188:191], v[120:123]
	v_mfma_f32_16x16x32_bf16 v[108:111], v[172:175], v[196:199], v[108:111]
	v_mfma_f32_16x16x32_bf16 v[104:107], v[180:183], v[196:199], v[104:107]
	v_mfma_f32_16x16x32_bf16 v[92:95], v[172:175], v[204:207], v[92:95]
	v_mfma_f32_16x16x32_bf16 v[88:91], v[180:183], v[204:207], v[88:91]
	v_mfma_f32_16x16x32_bf16 v[76:79], v[172:175], v[212:215], v[76:79]
	v_mfma_f32_16x16x32_bf16 v[64:67], v[180:183], v[212:215], v[64:67]
	s_add_i32 s34, s61, s42
	s_mov_b32 m0, s34
	s_barrier
	global_load_lds_dwordx4 v[216:217], off
	s_add_i32 m0, s34, 0x2000
	s_add_i32 s34, s62, s42
	global_load_lds_dwordx4 v[218:219], off
	s_mov_b32 m0, s34
	s_nop 0
	global_load_lds_dwordx4 v[246:247], off
	s_add_i32 m0, s34, 0x2000
	s_nop 0
	global_load_lds_dwordx4 v[248:249], off
	ds_read_b128 v[184:187], v153 offset:49152
	ds_read_b128 v[188:191], v153 offset:50176
	ds_read_b128 v[192:195], v153 offset:51200
	ds_read_b128 v[196:199], v153 offset:52224
	ds_read_b128 v[200:203], v153 offset:53248
	ds_read_b128 v[204:207], v153 offset:54272
	ds_read_b128 v[208:211], v153 offset:55296
	ds_read_b128 v[212:215], v153 offset:56320
	s_waitcnt vmcnt(6)
	s_waitcnt lgkmcnt(0)
	s_barrier
	s_waitcnt lgkmcnt(0)
	v_mfma_f32_16x16x32_bf16 v[56:59], v[144:147], v[184:187], v[56:59]
	v_mfma_f32_16x16x32_bf16 v[52:55], v[160:163], v[184:187], v[52:55]
	v_mfma_f32_16x16x32_bf16 v[40:43], v[144:147], v[192:195], v[40:43]
	v_mfma_f32_16x16x32_bf16 v[36:39], v[160:163], v[192:195], v[36:39]
	v_mfma_f32_16x16x32_bf16 v[24:27], v[144:147], v[200:203], v[24:27]
	v_mfma_f32_16x16x32_bf16 v[20:23], v[160:163], v[200:203], v[20:23]
	v_mfma_f32_16x16x32_bf16 v[8:11], v[144:147], v[208:211], v[8:11]
	v_mfma_f32_16x16x32_bf16 v[0:3], v[160:163], v[208:211], v[0:3]
	v_mfma_f32_16x16x32_bf16 v[56:59], v[156:159], v[188:191], v[56:59]
	v_mfma_f32_16x16x32_bf16 v[52:55], v[164:167], v[188:191], v[52:55]
	v_mfma_f32_16x16x32_bf16 v[40:43], v[156:159], v[196:199], v[40:43]
	v_mfma_f32_16x16x32_bf16 v[36:39], v[164:167], v[196:199], v[36:39]
	v_mfma_f32_16x16x32_bf16 v[24:27], v[156:159], v[204:207], v[24:27]
	v_mfma_f32_16x16x32_bf16 v[20:23], v[164:167], v[204:207], v[20:23]
	v_mfma_f32_16x16x32_bf16 v[8:11], v[156:159], v[212:215], v[8:11]
	v_mfma_f32_16x16x32_bf16 v[0:3], v[164:167], v[212:215], v[0:3]
	v_mfma_f32_16x16x32_bf16 v[60:63], v[168:171], v[184:187], v[60:63]
	v_mfma_f32_16x16x32_bf16 v[48:51], v[176:179], v[184:187], v[48:51]
	v_mfma_f32_16x16x32_bf16 v[44:47], v[168:171], v[192:195], v[44:47]
	v_mfma_f32_16x16x32_bf16 v[32:35], v[176:179], v[192:195], v[32:35]
	s_add_i32 s60, s60, 2
	v_mfma_f32_16x16x32_bf16 v[28:31], v[168:171], v[200:203], v[28:31]
	v_mfma_f32_16x16x32_bf16 v[16:19], v[176:179], v[200:203], v[16:19]
	s_add_u32 s28, s28, 0x100
	v_mfma_f32_16x16x32_bf16 v[12:15], v[168:171], v[208:211], v[12:15]
	v_mfma_f32_16x16x32_bf16 v[4:7], v[176:179], v[208:211], v[4:7]
	s_addc_u32 s29, s29, 0
	v_mfma_f32_16x16x32_bf16 v[60:63], v[172:175], v[188:191], v[60:63]
	v_mfma_f32_16x16x32_bf16 v[48:51], v[180:183], v[188:191], v[48:51]
	s_add_u32 s58, s58, 0x100
	v_mfma_f32_16x16x32_bf16 v[44:47], v[172:175], v[196:199], v[44:47]
	v_mfma_f32_16x16x32_bf16 v[32:35], v[180:183], v[196:199], v[32:35]
	s_addc_u32 s59, s59, 0
	v_mfma_f32_16x16x32_bf16 v[28:31], v[172:175], v[204:207], v[28:31]
	v_mfma_f32_16x16x32_bf16 v[16:19], v[180:183], v[204:207], v[16:19]
	v_mfma_f32_16x16x32_bf16 v[12:15], v[172:175], v[212:215], v[12:15]
	v_mfma_f32_16x16x32_bf16 v[4:7], v[180:183], v[212:215], v[4:7]
	s_barrier
	s_cmp_gt_u32 s60, 29
	s_cbranch_scc0 .LBB0_705
	s_and_b64 vcc, exec, s[10:11]
	s_cbranch_vccz .LBB0_708
	s_barrier

; #define PG8_STAGE(bufoff, gbase, voff) do { _Pragma("unroll") for (int _i = 0; _i < 2; ++_i) \
;         __builtin_amdgcn_global_load_lds((const unsigned*)((const char*)(gbase) + (voff)[_i]), (PG8_LAS unsigned*)(lds + (bufoff) + ldsw + _i * 8192), 16, 0, 0); } while (0)
; #define PG8_LDA(dst, b, h) do { _Pragma("unroll") for (int m = 0; m < 4; ++m) _Pragma("unroll") for (int k = 0; k < 2; ++k) dst[m][k] = *(const PG8_LAS bf16x8*)(lds + PG8_SA(b, h) + aoff + m * 2048 + k * 1024); } while (0)
; #define PG8_LDB(dst, b, h) do { _Pragma("unroll") for (int n = 0; n < 2; ++n) _Pragma("unroll") for (int k = 0; k < 2; ++k) dst[n][k] = *(const PG8_LAS bf16x8*)(lds + PG8_SB(b, h) + boff + n * 2048 + k * 1024); } while (0)
; #define PG8_MMA(ai, bj, At, Bt) do { __builtin_amdgcn_s_setprio(1); _Pragma("unroll") for (int m = 0; m < 4; ++m) _Pragma("unroll") for (int n = 0; n < 2; ++n) _Pragma("unroll") for (int k = 0; k < 2; ++k) \
;         acc[ai][bj][m][n] = __builtin_amdgcn_mfma_f32_16x16x32_bf16(Bt[n][k], At[m][k], acc[ai][bj][m][n], 0, 0, 0); __builtin_amdgcn_s_setprio(0); } while (0)
; #define PG8_WAIT_V(n) asm volatile("s_waitcnt vmcnt(" #n ")" ::: "memory")
; #define PG8_WAIT_L(n) asm volatile("s_waitcnt lgkmcnt(" #n ")" ::: "memory")
; #define PG8_BAR __builtin_amdgcn_s_barrier()
; #define PG8_SCHED __builtin_amdgcn_sched_barrier(0)
; template <class Epi, class Sched, bool ALIGN_EPI = false, bool SP2 = false>
; __device__ __forceinline__ void gemm_phase(PG8_LAS unsigned char* lds, const Gemm g, const Sched& S, const Epi& E) {
;     ...
;             PG8_LDB(B0, 0, 0); PG8_LDB(B1, 0, 1); PG8_SCHED; PG8_LDA(At, 0, 0); PG8_STAGE(PG8_SA(1, 1), a1 + hstep, voffA);
;             PG8_WAIT_V(8); PG8_WAIT_L(0); PG8_BAR; PG8_MMA(0, 0, At, B0); PG8_MMA(0, 1, At, B1); PG8_BAR; PG8_SCHED;
;             PG8_LDA(At, 0, 1); PG8_STAGE(PG8_SB(0, 0), b2, voffB); PG8_STAGE(PG8_SB(0, 1), b2 + hstep, voffB); PG8_STAGE(PG8_SA(0, 0), a2, voffA);
;             PG8_WAIT_V(8); PG8_WAIT_L(0); PG8_BAR; PG8_MMA(1, 0, At, B0); PG8_MMA(1, 1, At, B1); PG8_BAR; PG8_SCHED;
.LBB0_788:
	ds_read_b128 v[128:131], v189
	ds_read_b128 v[132:135], v189 offset:1024
	ds_read_b128 v[136:139], v189 offset:2048
	ds_read_b128 v[140:143], v189 offset:3072
	ds_read_b128 v[144:147], v190
	ds_read_b128 v[148:151], v190 offset:1024
	ds_read_b128 v[168:171], v190 offset:2048
	ds_read_b128 v[172:175], v190 offset:3072
	s_mov_b32 m0, s45
	s_nop 0
	global_load_lds_dwordx4 v[250:251], off
	s_mov_b32 m0, s46
	s_nop 0
	global_load_lds_dwordx4 v[252:253], off
	s_add_u32 s24, s22, 0x100
	s_addc_u32 s25, s23, 0
	s_cmpk_eq_i32 s58, 0x54
	s_cselect_b32 s31, s7, s25
	s_cselect_b32 s30, s6, s24
	s_cselect_b32 s29, s17, s57
	s_cselect_b32 s28, s16, s56
	v_lshl_add_u64 v[184:185], s[22:23], 0, v[160:161]
	s_add_i32 m0, s40, 0xc000
	s_nop 0
	global_load_lds_dwordx4 v[184:185], off
	v_lshl_add_u64 v[184:185], s[22:23], 0, v[162:163]
	s_add_i32 m0, s40, 0xe000
	s_nop 0
	global_load_lds_dwordx4 v[184:185], off
	ds_read_b128 v[176:179], v191
	ds_read_b128 v[180:183], v191 offset:1024
	ds_read_b128 v[192:195], v191 offset:2048
	ds_read_b128 v[196:199], v191 offset:3072
	ds_read_b128 v[200:203], v191 offset:4096
	ds_read_b128 v[204:207], v191 offset:5120
	ds_read_b128 v[208:211], v191 offset:6144
	ds_read_b128 v[212:215], v191 offset:7168
	s_waitcnt vmcnt(8)
	s_waitcnt lgkmcnt(0)
	s_barrier
	s_waitcnt lgkmcnt(0)
	v_mfma_f32_16x16x32_bf16 v[124:127], v[128:131], v[176:179], v[124:127]
	v_mfma_f32_16x16x32_bf16 v[120:123], v[136:139], v[176:179], v[120:123]
	s_add_u32 s22, s28, 0x160000
	v_mfma_f32_16x16x32_bf16 v[108:111], v[128:131], v[192:195], v[108:111]
	v_mfma_f32_16x16x32_bf16 v[104:107], v[136:139], v[192:195], v[104:107]
	s_addc_u32 s23, s29, 0
	v_mfma_f32_16x16x32_bf16 v[92:95], v[128:131], v[200:203], v[92:95]
	v_mfma_f32_16x16x32_bf16 v[88:91], v[136:139], v[200:203], v[88:91]
	v_lshl_add_u64 v[184:185], s[28:29], 0, v[154:155]
	v_mfma_f32_16x16x32_bf16 v[76:79], v[128:131], v[208:211], v[76:79]
	v_mfma_f32_16x16x32_bf16 v[72:75], v[136:139], v[208:211], v[72:75]
	v_lshl_add_u64 v[216:217], s[28:29], 0, v[158:159]
	v_mfma_f32_16x16x32_bf16 v[124:127], v[132:135], v[180:183], v[124:127]
	v_mfma_f32_16x16x32_bf16 v[120:123], v[140:143], v[180:183], v[120:123]
	v_lshl_add_u64 v[246:247], s[22:23], 0, v[154:155]
	v_mfma_f32_16x16x32_bf16 v[108:111], v[132:135], v[196:199], v[108:111]
	v_mfma_f32_16x16x32_bf16 v[104:107], v[140:143], v[196:199], v[104:107]
	v_lshl_add_u64 v[220:221], s[30:31], 0, v[156:157]
	v_mfma_f32_16x16x32_bf16 v[92:95], v[132:135], v[204:207], v[92:95]
	v_mfma_f32_16x16x32_bf16 v[88:91], v[140:143], v[204:207], v[88:91]
	v_lshl_add_u64 v[248:249], s[22:23], 0, v[158:159]
	v_mfma_f32_16x16x32_bf16 v[76:79], v[132:135], v[212:215], v[76:79]
	v_mfma_f32_16x16x32_bf16 v[72:75], v[140:143], v[212:215], v[72:75]
	v_lshl_add_u64 v[218:219], s[30:31], 0, v[152:153]
	v_mfma_f32_16x16x32_bf16 v[116:119], v[144:147], v[176:179], v[116:119]
	v_mfma_f32_16x16x32_bf16 v[112:115], v[168:171], v[176:179], v[112:115]
	v_mfma_f32_16x16x32_bf16 v[100:103], v[144:147], v[192:195], v[100:103]
	v_mfma_f32_16x16x32_bf16 v[96:99], v[168:171], v[192:195], v[96:99]
	v_mfma_f32_16x16x32_bf16 v[84:87], v[144:147], v[200:203], v[84:87]
	v_mfma_f32_16x16x32_bf16 v[80:83], v[168:171], v[200:203], v[80:83]
	v_mfma_f32_16x16x32_bf16 v[68:71], v[144:147], v[208:211], v[68:71]
	v_mfma_f32_16x16x32_bf16 v[64:67], v[168:171], v[208:211], v[64:67]
	v_mfma_f32_16x16x32_bf16 v[116:119], v[148:151], v[180:183], v[116:119]
	v_mfma_f32_16x16x32_bf16 v[112:115], v[172:175], v[180:183], v[112:115]
	v_mfma_f32_16x16x32_bf16 v[100:103], v[148:151], v[196:199], v[100:103]
	v_mfma_f32_16x16x32_bf16 v[96:99], v[172:175], v[196:199], v[96:99]
	v_mfma_f32_16x16x32_bf16 v[84:87], v[148:151], v[204:207], v[84:87]
	v_mfma_f32_16x16x32_bf16 v[80:83], v[172:175], v[204:207], v[80:83]
	v_mfma_f32_16x16x32_bf16 v[68:71], v[148:151], v[212:215], v[68:71]
	v_mfma_f32_16x16x32_bf16 v[64:67], v[172:175], v[212:215], v[64:67]
	s_add_i32 s22, s49, s39
	s_mov_b32 m0, s22
	s_barrier
	global_load_lds_dwordx4 v[184:185], off
	s_add_i32 m0, s22, 0x2000
	s_add_i32 s59, s50, s39
	global_load_lds_dwordx4 v[216:217], off
	s_mov_b32 m0, s59
	s_nop 0
	global_load_lds_dwordx4 v[246:247], off
	s_add_i32 m0, s59, 0x2000
	s_nop 0
	global_load_lds_dwordx4 v[248:249], off
	ds_read_b128 v[176:179], v191 offset:16384
	ds_read_b128 v[180:183], v191 offset:17408
	ds_read_b128 v[192:195], v191 offset:18432
	ds_read_b128 v[196:199], v191 offset:19456
	ds_read_b128 v[200:203], v191 offset:20480
	ds_read_b128 v[204:207], v191 offset:21504
	ds_read_b128 v[208:211], v191 offset:22528
	ds_read_b128 v[212:215], v191 offset:23552
	s_waitcnt vmcnt(6)
	s_waitcnt lgkmcnt(0)
	s_barrier
; #define PG8_STAGE(bufoff, gbase, voff) do { _Pragma("unroll") for (int _i = 0; _i < 2; ++_i) \
;         __builtin_amdgcn_global_load_lds((const unsigned*)((const char*)(gbase) + (voff)[_i]), (PG8_LAS unsigned*)(lds + (bufoff) + ldsw + _i * 8192), 16, 0, 0); } while (0)
; #define PG8_LDA(dst, b, h) do { _Pragma("unroll") for (int m = 0; m < 4; ++m) _Pragma("unroll") for (int k = 0; k < 2; ++k) dst[m][k] = *(const PG8_LAS bf16x8*)(lds + PG8_SA(b, h) + aoff + m * 2048 + k * 1024); } while (0)
; #define PG8_LDB(dst, b, h) do { _Pragma("unroll") for (int n = 0; n < 2; ++n) _Pragma("unroll") for (int k = 0; k < 2; ++k) dst[n][k] = *(const PG8_LAS bf16x8*)(lds + PG8_SB(b, h) + boff + n * 2048 + k * 1024); } while (0)
; #define PG8_MMA(ai, bj, At, Bt) do { __builtin_amdgcn_s_setprio(1); _Pragma("unroll") for (int m = 0; m < 4; ++m) _Pragma("unroll") for (int n = 0; n < 2; ++n) _Pragma("unroll") for (int k = 0; k < 2; ++k) \
;         acc[ai][bj][m][n] = __builtin_amdgcn_mfma_f32_16x16x32_bf16(Bt[n][k], At[m][k], acc[ai][bj][m][n], 0, 0, 0); __builtin_amdgcn_s_setprio(0); } while (0)
; #define PG8_WAIT_V(n) asm volatile("s_waitcnt vmcnt(" #n ")" ::: "memory")
; #define PG8_WAIT_L(n) asm volatile("s_waitcnt lgkmcnt(" #n ")" ::: "memory")
; #define PG8_BAR __builtin_amdgcn_s_barrier()
; #define PG8_SCHED __builtin_amdgcn_sched_barrier(0)
; template <class Epi, class Sched, bool ALIGN_EPI = false, bool SP2 = false>
; __device__ __forceinline__ void gemm_phase(PG8_LAS unsigned char* lds, const Gemm g, const Sched& S, const Epi& E) {
;     ...
;             PG8_WAIT_V(8); PG8_WAIT_L(0); PG8_BAR; PG8_MMA(1, 0, At, B0); PG8_MMA(1, 1, At, B1); PG8_BAR; PG8_SCHED;
;             PG8_LDB(B0, 1, 0); PG8_LDB(B1, 1, 1); PG8_SCHED; PG8_LDA(At, 1, 0); PG8_STAGE(PG8_SA(0, 1), a2 + hstep, voffA);
	s_waitcnt lgkmcnt(0)
	v_mfma_f32_16x16x32_bf16 v[60:63], v[128:131], v[176:179], v[60:63]
	v_mfma_f32_16x16x32_bf16 v[56:59], v[136:139], v[176:179], v[56:59]
	v_mfma_f32_16x16x32_bf16 v[44:47], v[128:131], v[192:195], v[44:47]
	v_mfma_f32_16x16x32_bf16 v[40:43], v[136:139], v[192:195], v[40:43]
	v_mfma_f32_16x16x32_bf16 v[28:31], v[128:131], v[200:203], v[28:31]
	v_mfma_f32_16x16x32_bf16 v[24:27], v[136:139], v[200:203], v[24:27]
	v_mfma_f32_16x16x32_bf16 v[12:15], v[128:131], v[208:211], v[12:15]
	v_mfma_f32_16x16x32_bf16 v[8:11], v[136:139], v[208:211], v[8:11]
	v_mfma_f32_16x16x32_bf16 v[60:63], v[132:135], v[180:183], v[60:63]
	v_mfma_f32_16x16x32_bf16 v[56:59], v[140:143], v[180:183], v[56:59]
	v_mfma_f32_16x16x32_bf16 v[44:47], v[132:135], v[196:199], v[44:47]
	v_mfma_f32_16x16x32_bf16 v[40:43], v[140:143], v[196:199], v[40:43]
	v_mfma_f32_16x16x32_bf16 v[28:31], v[132:135], v[204:207], v[28:31]
	v_mfma_f32_16x16x32_bf16 v[24:27], v[140:143], v[204:207], v[24:27]
	v_mfma_f32_16x16x32_bf16 v[12:15], v[132:135], v[212:215], v[12:15]
	v_mfma_f32_16x16x32_bf16 v[8:11], v[140:143], v[212:215], v[8:11]
	v_mfma_f32_16x16x32_bf16 v[52:55], v[144:147], v[176:179], v[52:55]
	v_mfma_f32_16x16x32_bf16 v[48:51], v[168:171], v[176:179], v[48:51]
	v_mfma_f32_16x16x32_bf16 v[36:39], v[144:147], v[192:195], v[36:39]
	v_mfma_f32_16x16x32_bf16 v[32:35], v[168:171], v[192:195], v[32:35]
	v_mfma_f32_16x16x32_bf16 v[20:23], v[144:147], v[200:203], v[20:23]
	v_mfma_f32_16x16x32_bf16 v[16:19], v[168:171], v[200:203], v[16:19]
	v_mfma_f32_16x16x32_bf16 v[4:7], v[144:147], v[208:211], v[4:7]
	v_mfma_f32_16x16x32_bf16 v[0:3], v[168:171], v[208:211], v[0:3]
	v_mfma_f32_16x16x32_bf16 v[52:55], v[148:151], v[180:183], v[52:55]
	v_mfma_f32_16x16x32_bf16 v[48:51], v[172:175], v[180:183], v[48:51]
	v_mfma_f32_16x16x32_bf16 v[36:39], v[148:151], v[196:199], v[36:39]
	v_mfma_f32_16x16x32_bf16 v[32:35], v[172:175], v[196:199], v[32:35]
	v_mfma_f32_16x16x32_bf16 v[20:23], v[148:151], v[204:207], v[20:23]
	v_mfma_f32_16x16x32_bf16 v[16:19], v[172:175], v[204:207], v[16:19]
	v_mfma_f32_16x16x32_bf16 v[4:7], v[148:151], v[212:215], v[4:7]
	v_mfma_f32_16x16x32_bf16 v[0:3], v[172:175], v[212:215], v[0:3]
	s_barrier
	s_add_i32 s59, 0, 0x18000
	s_add_i32 s60, 0, 0x1c000
	v_add_u32_e32 v140, s59, v187
	v_add_u32_e32 v172, s60, v187
	ds_read_b128 v[128:131], v140
	ds_read_b128 v[132:135], v140 offset:1024
	ds_read_b128 v[136:139], v140 offset:2048
	ds_read_b128 v[140:143], v140 offset:3072
	ds_read_b128 v[144:147], v172
	ds_read_b128 v[148:151], v172 offset:1024
	ds_read_b128 v[168:171], v172 offset:2048
	ds_read_b128 v[172:175], v172 offset:3072
	s_mov_b32 m0, s40
	s_nop 0
	global_load_lds_dwordx4 v[218:219], off
	s_mov_b32 m0, s41
	s_nop 0
	global_load_lds_dwordx4 v[220:221], off
	s_add_u32 s22, s30, 0x160000
	s_addc_u32 s23, s31, 0
	s_mov_b32 m0, s42
	v_lshl_add_u64 v[222:223], s[22:23], 0, v[152:153]
	global_load_lds_dwordx4 v[222:223], off
	v_lshl_add_u64 v[222:223], s[22:23], 0, v[156:157]
	s_mov_b32 m0, s43
	s_nop 0
	global_load_lds_dwordx4 v[222:223], off
	ds_read_b128 v[176:179], v191 offset:32768
	ds_read_b128 v[180:183], v191 offset:33792
	ds_read_b128 v[192:195], v191 offset:34816
	ds_read_b128 v[196:199], v191 offset:35840
	ds_read_b128 v[200:203], v191 offset:36864
	ds_read_b128 v[204:207], v191 offset:37888
	ds_read_b128 v[208:211], v191 offset:38912
	ds_read_b128 v[212:215], v191 offset:39936
	s_waitcnt vmcnt(8)
	s_waitcnt lgkmcnt(0)
	s_barrier
; #define PG8_STAGE(bufoff, gbase, voff) do { _Pragma("unroll") for (int _i = 0; _i < 2; ++_i) \
;         __builtin_amdgcn_global_load_lds((const unsigned*)((const char*)(gbase) + (voff)[_i]), (PG8_LAS unsigned*)(lds + (bufoff) + ldsw + _i * 8192), 16, 0, 0); } while (0)
; #define PG8_LDA(dst, b, h) do { _Pragma("unroll") for (int m = 0; m < 4; ++m) _Pragma("unroll") for (int k = 0; k < 2; ++k) dst[m][k] = *(const PG8_LAS bf16x8*)(lds + PG8_SA(b, h) + aoff + m * 2048 + k * 1024); } while (0)
; #define PG8_MMA(ai, bj, At, Bt) do { __builtin_amdgcn_s_setprio(1); _Pragma("unroll") for (int m = 0; m < 4; ++m) _Pragma("unroll") for (int n = 0; n < 2; ++n) _Pragma("unroll") for (int k = 0; k < 2; ++k) \
;         acc[ai][bj][m][n] = __builtin_amdgcn_mfma_f32_16x16x32_bf16(Bt[n][k], At[m][k], acc[ai][bj][m][n], 0, 0, 0); __builtin_amdgcn_s_setprio(0); } while (0)
; #define PG8_WAIT_V(n) asm volatile("s_waitcnt vmcnt(" #n ")" ::: "memory")
; #define PG8_WAIT_L(n) asm volatile("s_waitcnt lgkmcnt(" #n ")" ::: "memory")
; #define PG8_BAR __builtin_amdgcn_s_barrier()
; #define PG8_SCHED __builtin_amdgcn_sched_barrier(0)
; template <class Epi, class Sched, bool ALIGN_EPI = false, bool SP2 = false>
; __device__ __forceinline__ void gemm_phase(PG8_LAS unsigned char* lds, const Gemm g, const Sched& S, const Epi& E) {
;     ...
;             PG8_WAIT_V(8); PG8_WAIT_L(0); PG8_BAR; PG8_MMA(0, 0, At, B0); PG8_MMA(0, 1, At, B1); PG8_BAR; PG8_SCHED;
;             PG8_LDA(At, 1, 1); PG8_STAGE(PG8_SB(1, 0), b3, voffB); PG8_STAGE(PG8_SB(1, 1), b3 + hstep, voffB); PG8_STAGE(PG8_SA(1, 0), a3, voffA);
;             PG8_WAIT_V(8); PG8_WAIT_L(0); PG8_BAR; PG8_MMA(1, 0, At, B0); PG8_MMA(1, 1, At, B1); PG8_BAR; PG8_SCHED;
	s_waitcnt lgkmcnt(0)
	v_mfma_f32_16x16x32_bf16 v[124:127], v[128:131], v[176:179], v[124:127]
	v_mfma_f32_16x16x32_bf16 v[120:123], v[136:139], v[176:179], v[120:123]
	s_add_u32 s22, s28, 0x160080
	v_mfma_f32_16x16x32_bf16 v[108:111], v[128:131], v[192:195], v[108:111]
	v_mfma_f32_16x16x32_bf16 v[104:107], v[136:139], v[192:195], v[104:107]
	s_addc_u32 s23, s29, 0
	v_mfma_f32_16x16x32_bf16 v[92:95], v[128:131], v[200:203], v[92:95]
	v_mfma_f32_16x16x32_bf16 v[88:91], v[136:139], v[200:203], v[88:91]
	v_lshl_add_u64 v[184:185], v[184:185], 0, s[12:13]
	v_mfma_f32_16x16x32_bf16 v[76:79], v[128:131], v[208:211], v[76:79]
	v_mfma_f32_16x16x32_bf16 v[72:75], v[136:139], v[208:211], v[72:75]
	v_lshl_add_u64 v[216:217], v[216:217], 0, s[12:13]
	v_mfma_f32_16x16x32_bf16 v[124:127], v[132:135], v[180:183], v[124:127]
	v_mfma_f32_16x16x32_bf16 v[120:123], v[140:143], v[180:183], v[120:123]
	v_lshl_add_u64 v[246:247], s[22:23], 0, v[154:155]
	v_mfma_f32_16x16x32_bf16 v[108:111], v[132:135], v[196:199], v[108:111]
	v_mfma_f32_16x16x32_bf16 v[104:107], v[140:143], v[196:199], v[104:107]
	v_lshl_add_u64 v[248:249], s[22:23], 0, v[158:159]
	v_mfma_f32_16x16x32_bf16 v[92:95], v[132:135], v[204:207], v[92:95]
	v_mfma_f32_16x16x32_bf16 v[88:91], v[140:143], v[204:207], v[88:91]
	v_lshl_add_u64 v[250:251], v[218:219], 0, s[12:13]
	v_mfma_f32_16x16x32_bf16 v[76:79], v[132:135], v[212:215], v[76:79]
	v_mfma_f32_16x16x32_bf16 v[72:75], v[140:143], v[212:215], v[72:75]
	v_lshl_add_u64 v[252:253], v[220:221], 0, s[12:13]
	v_mfma_f32_16x16x32_bf16 v[116:119], v[144:147], v[176:179], v[116:119]
	v_mfma_f32_16x16x32_bf16 v[112:115], v[168:171], v[176:179], v[112:115]
	v_mfma_f32_16x16x32_bf16 v[100:103], v[144:147], v[192:195], v[100:103]
	v_mfma_f32_16x16x32_bf16 v[96:99], v[168:171], v[192:195], v[96:99]
	v_mfma_f32_16x16x32_bf16 v[84:87], v[144:147], v[200:203], v[84:87]
	v_mfma_f32_16x16x32_bf16 v[80:83], v[168:171], v[200:203], v[80:83]
	v_mfma_f32_16x16x32_bf16 v[68:71], v[144:147], v[208:211], v[68:71]
	v_mfma_f32_16x16x32_bf16 v[64:67], v[168:171], v[208:211], v[64:67]
	v_mfma_f32_16x16x32_bf16 v[116:119], v[148:151], v[180:183], v[116:119]
	v_mfma_f32_16x16x32_bf16 v[112:115], v[172:175], v[180:183], v[112:115]
	v_mfma_f32_16x16x32_bf16 v[100:103], v[148:151], v[196:199], v[100:103]
	v_mfma_f32_16x16x32_bf16 v[96:99], v[172:175], v[196:199], v[96:99]
	v_mfma_f32_16x16x32_bf16 v[84:87], v[148:151], v[204:207], v[84:87]
	v_mfma_f32_16x16x32_bf16 v[80:83], v[172:175], v[204:207], v[80:83]
	v_mfma_f32_16x16x32_bf16 v[68:71], v[148:151], v[212:215], v[68:71]
	v_mfma_f32_16x16x32_bf16 v[64:67], v[172:175], v[212:215], v[64:67]
	s_add_i32 s22, s59, s39
	s_mov_b32 m0, s22
	s_barrier
	global_load_lds_dwordx4 v[184:185], off
	s_add_i32 m0, s22, 0x2000
	s_add_i32 s28, s60, s39
	global_load_lds_dwordx4 v[216:217], off
	s_mov_b32 m0, s28
	s_nop 0
	global_load_lds_dwordx4 v[246:247], off
	s_add_i32 m0, s28, 0x2000
	s_nop 0
	global_load_lds_dwordx4 v[248:249], off
	ds_read_b128 v[176:179], v191 offset:49152
	ds_read_b128 v[180:183], v191 offset:50176
	ds_read_b128 v[192:195], v191 offset:51200
	ds_read_b128 v[196:199], v191 offset:52224
	ds_read_b128 v[200:203], v191 offset:53248
	ds_read_b128 v[204:207], v191 offset:54272
	ds_read_b128 v[208:211], v191 offset:55296
	ds_read_b128 v[212:215], v191 offset:56320
	s_waitcnt vmcnt(6)
	s_waitcnt lgkmcnt(0)
	s_barrier
	s_waitcnt lgkmcnt(0)
	v_mfma_f32_16x16x32_bf16 v[60:63], v[128:131], v[176:179], v[60:63]
	v_mfma_f32_16x16x32_bf16 v[56:59], v[136:139], v[176:179], v[56:59]
	v_mfma_f32_16x16x32_bf16 v[44:47], v[128:131], v[192:195], v[44:47]
	v_mfma_f32_16x16x32_bf16 v[40:43], v[136:139], v[192:195], v[40:43]
	v_mfma_f32_16x16x32_bf16 v[28:31], v[128:131], v[200:203], v[28:31]
	v_mfma_f32_16x16x32_bf16 v[24:27], v[136:139], v[200:203], v[24:27]
	v_mfma_f32_16x16x32_bf16 v[12:15], v[128:131], v[208:211], v[12:15]
	v_mfma_f32_16x16x32_bf16 v[8:11], v[136:139], v[208:211], v[8:11]
	v_mfma_f32_16x16x32_bf16 v[60:63], v[132:135], v[180:183], v[60:63]
	v_mfma_f32_16x16x32_bf16 v[56:59], v[140:143], v[180:183], v[56:59]
	v_mfma_f32_16x16x32_bf16 v[44:47], v[132:135], v[196:199], v[44:47]
	v_mfma_f32_16x16x32_bf16 v[40:43], v[140:143], v[196:199], v[40:43]
	v_mfma_f32_16x16x32_bf16 v[28:31], v[132:135], v[204:207], v[28:31]
	v_mfma_f32_16x16x32_bf16 v[24:27], v[140:143], v[204:207], v[24:27]
	v_mfma_f32_16x16x32_bf16 v[12:15], v[132:135], v[212:215], v[12:15]
	v_mfma_f32_16x16x32_bf16 v[8:11], v[140:143], v[212:215], v[8:11]
	v_mfma_f32_16x16x32_bf16 v[52:55], v[144:147], v[176:179], v[52:55]
	v_mfma_f32_16x16x32_bf16 v[48:51], v[168:171], v[176:179], v[48:51]
	v_mfma_f32_16x16x32_bf16 v[36:39], v[144:147], v[192:195], v[36:39]
	v_mfma_f32_16x16x32_bf16 v[32:35], v[168:171], v[192:195], v[32:35]
	s_add_i32 s58, s58, 2
	v_mfma_f32_16x16x32_bf16 v[20:23], v[144:147], v[200:203], v[20:23]
	v_mfma_f32_16x16x32_bf16 v[16:19], v[168:171], v[200:203], v[16:19]
	s_add_u32 s56, s56, 0x100
	v_mfma_f32_16x16x32_bf16 v[4:7], v[144:147], v[208:211], v[4:7]
	v_mfma_f32_16x16x32_bf16 v[0:3], v[168:171], v[208:211], v[0:3]
	s_addc_u32 s57, s57, 0
	v_mfma_f32_16x16x32_bf16 v[52:55], v[148:151], v[180:183], v[52:55]
	v_mfma_f32_16x16x32_bf16 v[48:51], v[172:175], v[180:183], v[48:51]
	v_mfma_f32_16x16x32_bf16 v[36:39], v[148:151], v[196:199], v[36:39]
	v_mfma_f32_16x16x32_bf16 v[32:35], v[172:175], v[196:199], v[32:35]
	v_mfma_f32_16x16x32_bf16 v[20:23], v[148:151], v[204:207], v[20:23]
	v_mfma_f32_16x16x32_bf16 v[16:19], v[172:175], v[204:207], v[16:19]
	v_mfma_f32_16x16x32_bf16 v[4:7], v[148:151], v[212:215], v[4:7]
	v_mfma_f32_16x16x32_bf16 v[0:3], v[172:175], v[212:215], v[0:3]
	s_barrier
	s_cmpk_gt_u32 s58, 0x55
	s_mov_b64 s[22:23], s[24:25]
	s_cbranch_scc0 .LBB0_788
	s_and_b64 vcc, exec, s[14:15]
	s_cbranch_vccz .LBB0_791
	s_barrier
